# plain GEMM tile epilogues (phases 2,6,9,13,16): packed 32-bit LDS staging via DPP quad swap + v_perm instead of per-value 2-byte LDS writes
# speedup vs baseline: 1.2699x; 1.0049x over previous
; __device__ __forceinline__ void gemm_nt_phase(const u16* A, int lda, const u16* Bt, int ldb, u16* C, int ldc,
;                               int Mt, int Nt, int K, int qcols, float qscale, u16* smem,
;                               u16* vtx = nullptr, u16* vtc = nullptr, u16* smv = nullptr) {
;     ...
;     int tid_ = threadIdx.x;
;     asm volatile("" : "+v"(tid_));
;     const int lane = tid_ & 63, wid = tid_ >> 6, wm = wid >> 1, wn = wid & 1;
;     if (vtx != nullptr && nt >= 8) {
;       u16* dst; unsigned tstride;
;       if (mt < 128) { dst = vtx + (long)(mt >> 5) * 1024 * 8192 + (mt & 31) * 256; tstride = 8192; }
;       else          { dst = vtc + (long)(mt - 128) * 1024 * 256; tstride = 256; }
; #pragma unroll
;       for (int i = 0; i < 2; ++i)
; #pragma unroll
;         for (int j = 0; j < 4; ++j)
; #pragma unroll
;           for (int rq = 0; rq < 4; ++rq) {
;             const int row = wm * 64 + i * 32 + 8 * rq + 4 * (lane >> 5);
;             const int hd = (nt - 8) * 256 + wn * 128 + j * 32 + (lane & 31);
;             const unsigned v0 = f2bf(acc[i][j][4 * rq + 0]), v1 = f2bf(acc[i][j][4 * rq + 1]);
;             const unsigned v2 = f2bf(acc[i][j][4 * rq + 2]), v3 = f2bf(acc[i][j][4 * rq + 3]);
;             *reinterpret_cast<uint2*>(&dst[(unsigned)(hd * tstride + row)]) = make_uint2(v0 | (v1 << 16), v2 | (v3 << 16));
;           }
;     } else {
;       char* wb = reinterpret_cast<char*>(smem) + wid * 17408;
; #pragma unroll
;       for (int i = 0; i < 2; ++i)
; #pragma unroll
;         for (int j = 0; j < 4; ++j)
; #pragma unroll
;           for (int r = 0; r < 16; ++r) {
;             const int row = i * 32 + (r & 3) + 8 * (r >> 2) + 4 * (lane >> 5);
;             const int col = j * 32 + (lane & 31);
;             *reinterpret_cast<u16*>(wb + row * 272 + col * 2) = f2bf(acc[i][j][r] * sc);
;           }
.LBB0_180:
	s_waitcnt lgkmcnt(0)
	v_mov_b32_e32 v128, v152
	s_waitcnt vmcnt(0)
	s_barrier
	v_ashrrev_i32_e32 v129, 6, v128
	v_lshrrev_b32_e32 v131, 3, v128
	v_mul_lo_u32 v130, v129, s18
	v_and_b32_e32 v131, 4, v131
	v_lshlrev_b32_e32 v132, 1, v128
	v_add_u32_e32 v130, 16, v130
	v_and_b32_e32 v132, 62, v132
	v_mul_u32_u24_e32 v131, 0x110, v131
	v_add3_u32 v131, v130, v132, v131
	v_and_b32_e32 v194, 1, v152
	v_mov_b32_e32 v193, 0x01000504
	v_mov_b32_e32 v195, 0x07060302
	v_cmp_eq_u32_e32 vcc, 1, v194
	v_mul_u32_u24_e32 v194, 0x10e, v194
	v_add_u32_e32 v192, v131, v194
	v_cndmask_b32_e32 v193, v193, v195, vcc
	v_cvt_pk_bf16_f32 v194, v112, v113
	v_cvt_pk_bf16_f32 v195, v96, v97
	v_cvt_pk_bf16_f32 v196, v80, v81
	v_cvt_pk_bf16_f32 v197, v64, v65
	v_mov_b32_dpp v198, v194 quad_perm:[1,0,3,2] row_mask:0xf bank_mask:0xf
	v_mov_b32_dpp v199, v195 quad_perm:[1,0,3,2] row_mask:0xf bank_mask:0xf
	v_mov_b32_dpp v200, v196 quad_perm:[1,0,3,2] row_mask:0xf bank_mask:0xf
	v_mov_b32_dpp v201, v197 quad_perm:[1,0,3,2] row_mask:0xf bank_mask:0xf
	v_perm_b32 v202, v194, v198, v193
	v_perm_b32 v203, v195, v199, v193
	v_perm_b32 v206, v196, v200, v193
	v_perm_b32 v207, v197, v201, v193
	ds_write_b32 v192, v202 offset:0
	ds_write_b32 v192, v203 offset:64
	ds_write_b32 v192, v206 offset:128
	ds_write_b32 v192, v207 offset:192
	v_cvt_pk_bf16_f32 v194, v114, v115
	v_cvt_pk_bf16_f32 v195, v98, v99
	v_cvt_pk_bf16_f32 v196, v82, v83
	v_cvt_pk_bf16_f32 v197, v66, v67
	v_mov_b32_dpp v198, v194 quad_perm:[1,0,3,2] row_mask:0xf bank_mask:0xf
	v_mov_b32_dpp v199, v195 quad_perm:[1,0,3,2] row_mask:0xf bank_mask:0xf
	v_mov_b32_dpp v200, v196 quad_perm:[1,0,3,2] row_mask:0xf bank_mask:0xf
	v_mov_b32_dpp v201, v197 quad_perm:[1,0,3,2] row_mask:0xf bank_mask:0xf
	v_perm_b32 v202, v194, v198, v193
	v_perm_b32 v203, v195, v199, v193
	v_perm_b32 v206, v196, v200, v193
	v_perm_b32 v207, v197, v201, v193
	ds_write_b32 v192, v202 offset:544
	ds_write_b32 v192, v203 offset:608
	ds_write_b32 v192, v206 offset:672
	ds_write_b32 v192, v207 offset:736
	v_cvt_pk_bf16_f32 v194, v116, v117
	v_cvt_pk_bf16_f32 v195, v100, v101
	v_cvt_pk_bf16_f32 v196, v84, v85
	v_cvt_pk_bf16_f32 v197, v68, v69
	v_mov_b32_dpp v198, v194 quad_perm:[1,0,3,2] row_mask:0xf bank_mask:0xf
	v_mov_b32_dpp v199, v195 quad_perm:[1,0,3,2] row_mask:0xf bank_mask:0xf
	v_mov_b32_dpp v200, v196 quad_perm:[1,0,3,2] row_mask:0xf bank_mask:0xf
	v_mov_b32_dpp v201, v197 quad_perm:[1,0,3,2] row_mask:0xf bank_mask:0xf
	v_perm_b32 v202, v194, v198, v193
	v_perm_b32 v203, v195, v199, v193
	v_perm_b32 v206, v196, v200, v193
	v_perm_b32 v207, v197, v201, v193
	ds_write_b32 v192, v202 offset:2176
	ds_write_b32 v192, v203 offset:2240
	ds_write_b32 v192, v206 offset:2304
	ds_write_b32 v192, v207 offset:2368
	v_cvt_pk_bf16_f32 v194, v118, v119
	v_cvt_pk_bf16_f32 v195, v102, v103
	v_cvt_pk_bf16_f32 v196, v86, v87
	v_cvt_pk_bf16_f32 v197, v70, v71
	v_mov_b32_dpp v198, v194 quad_perm:[1,0,3,2] row_mask:0xf bank_mask:0xf
	v_mov_b32_dpp v199, v195 quad_perm:[1,0,3,2] row_mask:0xf bank_mask:0xf
	v_mov_b32_dpp v200, v196 quad_perm:[1,0,3,2] row_mask:0xf bank_mask:0xf
	v_mov_b32_dpp v201, v197 quad_perm:[1,0,3,2] row_mask:0xf bank_mask:0xf
	v_perm_b32 v202, v194, v198, v193
	v_perm_b32 v203, v195, v199, v193
	v_perm_b32 v206, v196, v200, v193
	v_perm_b32 v207, v197, v201, v193
	ds_write_b32 v192, v202 offset:2720
	ds_write_b32 v192, v203 offset:2784
	ds_write_b32 v192, v206 offset:2848
	ds_write_b32 v192, v207 offset:2912
	v_cvt_pk_bf16_f32 v194, v120, v121
	v_cvt_pk_bf16_f32 v195, v104, v105
	v_cvt_pk_bf16_f32 v196, v88, v89
	v_cvt_pk_bf16_f32 v197, v72, v73
	v_mov_b32_dpp v198, v194 quad_perm:[1,0,3,2] row_mask:0xf bank_mask:0xf
	v_mov_b32_dpp v199, v195 quad_perm:[1,0,3,2] row_mask:0xf bank_mask:0xf
	v_mov_b32_dpp v200, v196 quad_perm:[1,0,3,2] row_mask:0xf bank_mask:0xf
	v_mov_b32_dpp v201, v197 quad_perm:[1,0,3,2] row_mask:0xf bank_mask:0xf
	v_perm_b32 v202, v194, v198, v193
	v_perm_b32 v203, v195, v199, v193
	v_perm_b32 v206, v196, v200, v193
	v_perm_b32 v207, v197, v201, v193
	ds_write_b32 v192, v202 offset:4352
	ds_write_b32 v192, v203 offset:4416
	ds_write_b32 v192, v206 offset:4480
	ds_write_b32 v192, v207 offset:4544
	v_cvt_pk_bf16_f32 v194, v122, v123
	v_cvt_pk_bf16_f32 v195, v106, v107
	v_cvt_pk_bf16_f32 v196, v90, v91
	v_cvt_pk_bf16_f32 v197, v74, v75
	v_mov_b32_dpp v198, v194 quad_perm:[1,0,3,2] row_mask:0xf bank_mask:0xf
	v_mov_b32_dpp v199, v195 quad_perm:[1,0,3,2] row_mask:0xf bank_mask:0xf
	v_mov_b32_dpp v200, v196 quad_perm:[1,0,3,2] row_mask:0xf bank_mask:0xf
	v_mov_b32_dpp v201, v197 quad_perm:[1,0,3,2] row_mask:0xf bank_mask:0xf
	v_perm_b32 v202, v194, v198, v193
	v_perm_b32 v203, v195, v199, v193
	v_perm_b32 v206, v196, v200, v193
	v_perm_b32 v207, v197, v201, v193
	ds_write_b32 v192, v202 offset:4896
	ds_write_b32 v192, v203 offset:4960
	ds_write_b32 v192, v206 offset:5024
	ds_write_b32 v192, v207 offset:5088
	v_cvt_pk_bf16_f32 v194, v124, v125
	v_cvt_pk_bf16_f32 v195, v108, v109
	v_cvt_pk_bf16_f32 v196, v92, v93
	v_cvt_pk_bf16_f32 v197, v76, v77
	v_mov_b32_dpp v198, v194 quad_perm:[1,0,3,2] row_mask:0xf bank_mask:0xf
	v_mov_b32_dpp v199, v195 quad_perm:[1,0,3,2] row_mask:0xf bank_mask:0xf
	v_mov_b32_dpp v200, v196 quad_perm:[1,0,3,2] row_mask:0xf bank_mask:0xf
	v_mov_b32_dpp v201, v197 quad_perm:[1,0,3,2] row_mask:0xf bank_mask:0xf
	v_perm_b32 v202, v194, v198, v193
	v_perm_b32 v203, v195, v199, v193
	v_perm_b32 v206, v196, v200, v193
	v_perm_b32 v207, v197, v201, v193
	ds_write_b32 v192, v202 offset:6528
	ds_write_b32 v192, v203 offset:6592
	ds_write_b32 v192, v206 offset:6656
	ds_write_b32 v192, v207 offset:6720
; __device__ __forceinline__ void gemm_nt_phase(const u16* A, int lda, const u16* Bt, int ldb, u16* C, int ldc,
;                               int Mt, int Nt, int K, int qcols, float qscale, u16* smem,
;                               u16* vtx = nullptr, u16* vtc = nullptr, u16* smv = nullptr) {
;     ...
;       char* wb = reinterpret_cast<char*>(smem) + wid * 17408;
; #pragma unroll
;       for (int i = 0; i < 2; ++i)
; #pragma unroll
;         for (int j = 0; j < 4; ++j)
; #pragma unroll
;           for (int r = 0; r < 16; ++r) {
;             const int row = i * 32 + (r & 3) + 8 * (r >> 2) + 4 * (lane >> 5);
;             const int col = j * 32 + (lane & 31);
;             *reinterpret_cast<u16*>(wb + row * 272 + col * 2) = f2bf(acc[i][j][r] * sc);
;           }
;       asm volatile("s_waitcnt lgkmcnt(0)" ::: "memory");
	v_cvt_pk_bf16_f32 v194, v126, v127
	v_cvt_pk_bf16_f32 v195, v110, v111
	v_cvt_pk_bf16_f32 v196, v94, v95
	v_cvt_pk_bf16_f32 v197, v78, v79
	v_mov_b32_dpp v198, v194 quad_perm:[1,0,3,2] row_mask:0xf bank_mask:0xf
	v_mov_b32_dpp v199, v195 quad_perm:[1,0,3,2] row_mask:0xf bank_mask:0xf
	v_mov_b32_dpp v200, v196 quad_perm:[1,0,3,2] row_mask:0xf bank_mask:0xf
	v_mov_b32_dpp v201, v197 quad_perm:[1,0,3,2] row_mask:0xf bank_mask:0xf
	v_perm_b32 v202, v194, v198, v193
	v_perm_b32 v203, v195, v199, v193
	v_perm_b32 v206, v196, v200, v193
	v_perm_b32 v207, v197, v201, v193
	ds_write_b32 v192, v202 offset:7072
	ds_write_b32 v192, v203 offset:7136
	ds_write_b32 v192, v206 offset:7200
	ds_write_b32 v192, v207 offset:7264
	v_cvt_pk_bf16_f32 v194, v48, v49
	v_cvt_pk_bf16_f32 v195, v32, v33
	v_cvt_pk_bf16_f32 v196, v16, v17
	v_cvt_pk_bf16_f32 v197, v0, v1
	v_mov_b32_dpp v198, v194 quad_perm:[1,0,3,2] row_mask:0xf bank_mask:0xf
	v_mov_b32_dpp v199, v195 quad_perm:[1,0,3,2] row_mask:0xf bank_mask:0xf
	v_mov_b32_dpp v200, v196 quad_perm:[1,0,3,2] row_mask:0xf bank_mask:0xf
	v_mov_b32_dpp v201, v197 quad_perm:[1,0,3,2] row_mask:0xf bank_mask:0xf
	v_perm_b32 v202, v194, v198, v193
	v_perm_b32 v203, v195, v199, v193
	v_perm_b32 v206, v196, v200, v193
	v_perm_b32 v207, v197, v201, v193
	ds_write_b32 v192, v202 offset:8704
	ds_write_b32 v192, v203 offset:8768
	ds_write_b32 v192, v206 offset:8832
	ds_write_b32 v192, v207 offset:8896
	v_cvt_pk_bf16_f32 v194, v50, v51
	v_cvt_pk_bf16_f32 v195, v34, v35
	v_cvt_pk_bf16_f32 v196, v18, v19
	v_cvt_pk_bf16_f32 v197, v2, v3
	v_mov_b32_dpp v198, v194 quad_perm:[1,0,3,2] row_mask:0xf bank_mask:0xf
	v_mov_b32_dpp v199, v195 quad_perm:[1,0,3,2] row_mask:0xf bank_mask:0xf
	v_mov_b32_dpp v200, v196 quad_perm:[1,0,3,2] row_mask:0xf bank_mask:0xf
	v_mov_b32_dpp v201, v197 quad_perm:[1,0,3,2] row_mask:0xf bank_mask:0xf
	v_perm_b32 v202, v194, v198, v193
	v_perm_b32 v203, v195, v199, v193
	v_perm_b32 v206, v196, v200, v193
	v_perm_b32 v207, v197, v201, v193
	ds_write_b32 v192, v202 offset:9248
	ds_write_b32 v192, v203 offset:9312
	ds_write_b32 v192, v206 offset:9376
	ds_write_b32 v192, v207 offset:9440
	v_cvt_pk_bf16_f32 v194, v52, v53
	v_cvt_pk_bf16_f32 v195, v36, v37
	v_cvt_pk_bf16_f32 v196, v20, v21
	v_cvt_pk_bf16_f32 v197, v4, v5
	v_mov_b32_dpp v198, v194 quad_perm:[1,0,3,2] row_mask:0xf bank_mask:0xf
	v_mov_b32_dpp v199, v195 quad_perm:[1,0,3,2] row_mask:0xf bank_mask:0xf
	v_mov_b32_dpp v200, v196 quad_perm:[1,0,3,2] row_mask:0xf bank_mask:0xf
	v_mov_b32_dpp v201, v197 quad_perm:[1,0,3,2] row_mask:0xf bank_mask:0xf
	v_perm_b32 v202, v194, v198, v193
	v_perm_b32 v203, v195, v199, v193
	v_perm_b32 v206, v196, v200, v193
	v_perm_b32 v207, v197, v201, v193
	ds_write_b32 v192, v202 offset:10880
	ds_write_b32 v192, v203 offset:10944
	ds_write_b32 v192, v206 offset:11008
	ds_write_b32 v192, v207 offset:11072
	v_cvt_pk_bf16_f32 v194, v54, v55
	v_cvt_pk_bf16_f32 v195, v38, v39
	v_cvt_pk_bf16_f32 v196, v22, v23
	v_cvt_pk_bf16_f32 v197, v6, v7
	v_mov_b32_dpp v198, v194 quad_perm:[1,0,3,2] row_mask:0xf bank_mask:0xf
	v_mov_b32_dpp v199, v195 quad_perm:[1,0,3,2] row_mask:0xf bank_mask:0xf
	v_mov_b32_dpp v200, v196 quad_perm:[1,0,3,2] row_mask:0xf bank_mask:0xf
	v_mov_b32_dpp v201, v197 quad_perm:[1,0,3,2] row_mask:0xf bank_mask:0xf
	v_perm_b32 v202, v194, v198, v193
	v_perm_b32 v203, v195, v199, v193
	v_perm_b32 v206, v196, v200, v193
	v_perm_b32 v207, v197, v201, v193
	ds_write_b32 v192, v202 offset:11424
	ds_write_b32 v192, v203 offset:11488
	ds_write_b32 v192, v206 offset:11552
	ds_write_b32 v192, v207 offset:11616
	v_cvt_pk_bf16_f32 v194, v56, v57
	v_cvt_pk_bf16_f32 v195, v40, v41
	v_cvt_pk_bf16_f32 v196, v24, v25
	v_cvt_pk_bf16_f32 v197, v8, v9
	v_mov_b32_dpp v198, v194 quad_perm:[1,0,3,2] row_mask:0xf bank_mask:0xf
	v_mov_b32_dpp v199, v195 quad_perm:[1,0,3,2] row_mask:0xf bank_mask:0xf
	v_mov_b32_dpp v200, v196 quad_perm:[1,0,3,2] row_mask:0xf bank_mask:0xf
	v_mov_b32_dpp v201, v197 quad_perm:[1,0,3,2] row_mask:0xf bank_mask:0xf
	v_perm_b32 v202, v194, v198, v193
	v_perm_b32 v203, v195, v199, v193
	v_perm_b32 v206, v196, v200, v193
	v_perm_b32 v207, v197, v201, v193
	ds_write_b32 v192, v202 offset:13056
	ds_write_b32 v192, v203 offset:13120
	ds_write_b32 v192, v206 offset:13184
	ds_write_b32 v192, v207 offset:13248
	v_cvt_pk_bf16_f32 v194, v58, v59
	v_cvt_pk_bf16_f32 v195, v42, v43
	v_cvt_pk_bf16_f32 v196, v26, v27
	v_cvt_pk_bf16_f32 v197, v10, v11
	v_mov_b32_dpp v198, v194 quad_perm:[1,0,3,2] row_mask:0xf bank_mask:0xf
	v_mov_b32_dpp v199, v195 quad_perm:[1,0,3,2] row_mask:0xf bank_mask:0xf
	v_mov_b32_dpp v200, v196 quad_perm:[1,0,3,2] row_mask:0xf bank_mask:0xf
	v_mov_b32_dpp v201, v197 quad_perm:[1,0,3,2] row_mask:0xf bank_mask:0xf
	v_perm_b32 v202, v194, v198, v193
	v_perm_b32 v203, v195, v199, v193
	v_perm_b32 v206, v196, v200, v193
	v_perm_b32 v207, v197, v201, v193
	ds_write_b32 v192, v202 offset:13600
	ds_write_b32 v192, v203 offset:13664
	ds_write_b32 v192, v206 offset:13728
	ds_write_b32 v192, v207 offset:13792
	v_cvt_pk_bf16_f32 v194, v60, v61
	v_cvt_pk_bf16_f32 v195, v44, v45
	v_cvt_pk_bf16_f32 v196, v28, v29
	v_cvt_pk_bf16_f32 v197, v12, v13
	v_mov_b32_dpp v198, v194 quad_perm:[1,0,3,2] row_mask:0xf bank_mask:0xf
	v_mov_b32_dpp v199, v195 quad_perm:[1,0,3,2] row_mask:0xf bank_mask:0xf
	v_mov_b32_dpp v200, v196 quad_perm:[1,0,3,2] row_mask:0xf bank_mask:0xf
	v_mov_b32_dpp v201, v197 quad_perm:[1,0,3,2] row_mask:0xf bank_mask:0xf
	v_perm_b32 v202, v194, v198, v193
	v_perm_b32 v203, v195, v199, v193
	v_perm_b32 v206, v196, v200, v193
	v_perm_b32 v207, v197, v201, v193
	ds_write_b32 v192, v202 offset:15232
	ds_write_b32 v192, v203 offset:15296
	ds_write_b32 v192, v206 offset:15360
	ds_write_b32 v192, v207 offset:15424
	v_cvt_pk_bf16_f32 v194, v62, v63
	v_cvt_pk_bf16_f32 v195, v46, v47
	v_cvt_pk_bf16_f32 v196, v30, v31
	v_cvt_pk_bf16_f32 v197, v14, v15
	v_mov_b32_dpp v198, v194 quad_perm:[1,0,3,2] row_mask:0xf bank_mask:0xf
	v_mov_b32_dpp v199, v195 quad_perm:[1,0,3,2] row_mask:0xf bank_mask:0xf
	v_mov_b32_dpp v200, v196 quad_perm:[1,0,3,2] row_mask:0xf bank_mask:0xf
	v_mov_b32_dpp v201, v197 quad_perm:[1,0,3,2] row_mask:0xf bank_mask:0xf
	v_perm_b32 v202, v194, v198, v193
	v_perm_b32 v203, v195, v199, v193
	v_perm_b32 v206, v196, v200, v193
	v_perm_b32 v207, v197, v201, v193
	ds_write_b32 v192, v202 offset:15776
	ds_write_b32 v192, v203 offset:15840
	ds_write_b32 v192, v206 offset:15904
	ds_write_b32 v192, v207 offset:15968
	v_and_b32_e32 v0, 15, v128
	v_lshlrev_b32_e32 v1, 4, v0
	v_lshlrev_b32_e32 v2, 7, v129
	v_lshlrev_b32_e32 v0, 3, v0
	v_bfe_u32 v5, v128, 4, 2
	s_lshl_b32 s8, s8, 8
	s_mul_hi_i32 s7, s6, 0xc0000
	s_mul_i32 s6, s6, 0xc0000
	v_and_or_b32 v10, v2, s17, v0
	v_mul_u32_u24_e32 v0, 0x110, v5
	s_add_u32 s10, s90, s6
	s_waitcnt lgkmcnt(0)
; __device__ __forceinline__ void gemm_nt_phase(const u16* A, int lda, const u16* Bt, int ldb, u16* C, int ldc,
;                               int Mt, int Nt, int K, int qcols, float qscale, u16* smem,
;                               u16* vtx = nullptr, u16* vtc = nullptr, u16* smv = nullptr) {
;     ...
;       asm volatile("s_waitcnt lgkmcnt(0)" ::: "memory");
; #pragma unroll
;       for (int q = 0; q < 16; ++q) {
;         const int idx = q * 64 + lane, row = idx >> 4, c16 = idx & 15;
;         const uint4 v = *reinterpret_cast<const uint4*>(wb + row * 272 + c16 * 16);
;         *reinterpret_cast<uint4*>(&Cb[(unsigned)((wm * 64 + row) * ldc + wn * 128 + c16 * 8)]) = v;
;       }
;     }
;     __syncthreads();
	v_add3_u32 v11, v130, v1, v0
	s_addc_u32 s11, s91, s7
	s_ashr_i32 s9, s8, 31
	v_ashrrev_i32_e32 v4, 1, v128
	ds_read_b128 v[0:3], v11
	s_lshl_b64 s[6:7], s[8:9], 1
	v_and_or_b32 v12, v4, s19, v5
	s_add_u32 s6, s10, s6
	v_mul_lo_u32 v4, v12, s20
	s_addc_u32 s7, s11, s7
	v_or_b32_e32 v154, v10, v4
	v_lshl_add_u64 v[8:9], v[154:155], 1, s[6:7]
	ds_read_b128 v[4:7], v11 offset:1088
	s_waitcnt lgkmcnt(1)
	global_store_dwordx4 v[8:9], v[0:3], off
	s_add_i32 s21, s21, s96
	s_cmp_lt_i32 s21, s3
	v_or_b32_e32 v0, 4, v12
	v_mul_lo_u32 v0, v0, s20
	v_or_b32_e32 v154, v0, v10
	v_lshl_add_u64 v[0:1], v[154:155], 1, s[6:7]
	s_waitcnt lgkmcnt(0)
	global_store_dwordx4 v[0:1], v[4:7], off
	ds_read_b128 v[0:3], v11 offset:2176
	s_nop 0
	v_or_b32_e32 v4, 8, v12
	v_mul_lo_u32 v4, v4, s20
	v_or_b32_e32 v154, v4, v10
	v_lshl_add_u64 v[8:9], v[154:155], 1, s[6:7]
	ds_read_b128 v[4:7], v11 offset:3264
	s_waitcnt lgkmcnt(1)
	global_store_dwordx4 v[8:9], v[0:3], off
	s_nop 1
	v_or_b32_e32 v0, 12, v12
	v_mul_lo_u32 v0, v0, s20
	v_or_b32_e32 v154, v0, v10
	v_lshl_add_u64 v[0:1], v[154:155], 1, s[6:7]
	s_waitcnt lgkmcnt(0)
	global_store_dwordx4 v[0:1], v[4:7], off
	ds_read_b128 v[0:3], v11 offset:4352
	s_nop 0
	v_or_b32_e32 v4, 16, v12
	v_mul_lo_u32 v4, v4, s20
	v_or_b32_e32 v154, v4, v10
	v_lshl_add_u64 v[8:9], v[154:155], 1, s[6:7]
	ds_read_b128 v[4:7], v11 offset:5440
	s_waitcnt lgkmcnt(1)
	global_store_dwordx4 v[8:9], v[0:3], off
	s_nop 1
	v_or_b32_e32 v0, 20, v12
	v_mul_lo_u32 v0, v0, s20
	v_or_b32_e32 v154, v0, v10
	v_lshl_add_u64 v[0:1], v[154:155], 1, s[6:7]
	s_waitcnt lgkmcnt(0)
	global_store_dwordx4 v[0:1], v[4:7], off
	ds_read_b128 v[0:3], v11 offset:6528
	s_nop 0
	v_or_b32_e32 v4, 24, v12
	v_mul_lo_u32 v4, v4, s20
	v_or_b32_e32 v154, v4, v10
	v_lshl_add_u64 v[8:9], v[154:155], 1, s[6:7]
	ds_read_b128 v[4:7], v11 offset:7616
	s_waitcnt lgkmcnt(1)
	global_store_dwordx4 v[8:9], v[0:3], off
	s_nop 1
	v_or_b32_e32 v0, 28, v12
	v_mul_lo_u32 v0, v0, s20
	v_or_b32_e32 v154, v0, v10
	v_lshl_add_u64 v[0:1], v[154:155], 1, s[6:7]
	s_waitcnt lgkmcnt(0)
	global_store_dwordx4 v[0:1], v[4:7], off
	ds_read_b128 v[0:3], v11 offset:8704
	s_nop 0
	v_or_b32_e32 v4, 32, v12
	v_mul_lo_u32 v4, v4, s20
	v_or_b32_e32 v154, v4, v10
	v_lshl_add_u64 v[8:9], v[154:155], 1, s[6:7]
	ds_read_b128 v[4:7], v11 offset:9792
	s_waitcnt lgkmcnt(1)
	global_store_dwordx4 v[8:9], v[0:3], off
	s_nop 1
	v_or_b32_e32 v0, 36, v12
	v_mul_lo_u32 v0, v0, s20
	v_or_b32_e32 v154, v0, v10
	v_lshl_add_u64 v[0:1], v[154:155], 1, s[6:7]
	s_waitcnt lgkmcnt(0)
	global_store_dwordx4 v[0:1], v[4:7], off
	ds_read_b128 v[0:3], v11 offset:10880
	s_nop 0
	v_or_b32_e32 v4, 40, v12
	v_mul_lo_u32 v4, v4, s20
	v_or_b32_e32 v154, v4, v10
	v_lshl_add_u64 v[8:9], v[154:155], 1, s[6:7]
	ds_read_b128 v[4:7], v11 offset:11968
	s_waitcnt lgkmcnt(1)
	global_store_dwordx4 v[8:9], v[0:3], off
	s_nop 1
	v_or_b32_e32 v0, 44, v12
	v_mul_lo_u32 v0, v0, s20
	v_or_b32_e32 v154, v0, v10
	v_lshl_add_u64 v[0:1], v[154:155], 1, s[6:7]
	s_waitcnt lgkmcnt(0)
	global_store_dwordx4 v[0:1], v[4:7], off
	ds_read_b128 v[0:3], v11 offset:13056
	s_nop 0
	v_or_b32_e32 v4, 48, v12
	v_mul_lo_u32 v4, v4, s20
	v_or_b32_e32 v154, v4, v10
	v_lshl_add_u64 v[8:9], v[154:155], 1, s[6:7]
	ds_read_b128 v[4:7], v11 offset:14144
	s_waitcnt lgkmcnt(1)
	global_store_dwordx4 v[8:9], v[0:3], off
	s_nop 1
	v_or_b32_e32 v0, 52, v12
	v_mul_lo_u32 v0, v0, s20
	v_or_b32_e32 v154, v0, v10
	v_lshl_add_u64 v[0:1], v[154:155], 1, s[6:7]
	s_waitcnt lgkmcnt(0)
	global_store_dwordx4 v[0:1], v[4:7], off
	ds_read_b128 v[0:3], v11 offset:15232
	s_nop 0
	v_or_b32_e32 v4, 56, v12
	v_mul_lo_u32 v4, v4, s20
	v_or_b32_e32 v154, v4, v10
	v_lshl_add_u64 v[8:9], v[154:155], 1, s[6:7]
	ds_read_b128 v[4:7], v11 offset:16320
	s_waitcnt lgkmcnt(1)
	global_store_dwordx4 v[8:9], v[0:3], off
	s_nop 1
	v_or_b32_e32 v0, 60, v12
	v_mul_lo_u32 v0, v0, s20
	v_or_b32_e32 v154, v0, v10
	v_lshl_add_u64 v[0:1], v[154:155], 1, s[6:7]
	s_waitcnt lgkmcnt(0)
	global_store_dwordx4 v[0:1], v[4:7], off
	s_barrier
	s_cbranch_scc0 .LBB0_229

; __device__ __forceinline__ void gemm_nt_phase(const u16* A, int lda, const u16* Bt, int ldb, u16* C, int ldc,
;                               int Mt, int Nt, int K, int qcols, float qscale, u16* smem,
;                               u16* vtx = nullptr, u16* vtc = nullptr, u16* smv = nullptr) {
;     ...
;     int tid_ = threadIdx.x;
;     asm volatile("" : "+v"(tid_));
;     const int lane = tid_ & 63, wid = tid_ >> 6, wm = wid >> 1, wn = wid & 1;
;     if (vtx != nullptr && nt >= 8) {
;       u16* dst; unsigned tstride;
;       if (mt < 128) { dst = vtx + (long)(mt >> 5) * 1024 * 8192 + (mt & 31) * 256; tstride = 8192; }
;       else          { dst = vtc + (long)(mt - 128) * 1024 * 256; tstride = 256; }
; #pragma unroll
;       for (int i = 0; i < 2; ++i)
; #pragma unroll
;         for (int j = 0; j < 4; ++j)
; #pragma unroll
;           for (int rq = 0; rq < 4; ++rq) {
;             const int row = wm * 64 + i * 32 + 8 * rq + 4 * (lane >> 5);
;             const int hd = (nt - 8) * 256 + wn * 128 + j * 32 + (lane & 31);
;             const unsigned v0 = f2bf(acc[i][j][4 * rq + 0]), v1 = f2bf(acc[i][j][4 * rq + 1]);
;             const unsigned v2 = f2bf(acc[i][j][4 * rq + 2]), v3 = f2bf(acc[i][j][4 * rq + 3]);
;             *reinterpret_cast<uint2*>(&dst[(unsigned)(hd * tstride + row)]) = make_uint2(v0 | (v1 << 16), v2 | (v3 << 16));
;           }
;     } else {
;       char* wb = reinterpret_cast<char*>(smem) + wid * 17408;
; #pragma unroll
;       for (int i = 0; i < 2; ++i)
; #pragma unroll
;         for (int j = 0; j < 4; ++j)
; #pragma unroll
;           for (int r = 0; r < 16; ++r) {
;             const int row = i * 32 + (r & 3) + 8 * (r >> 2) + 4 * (lane >> 5);
;             const int col = j * 32 + (lane & 31);
;             *reinterpret_cast<u16*>(wb + row * 272 + col * 2) = f2bf(acc[i][j][r] * sc);
;           }
.LBB0_818:
	s_waitcnt lgkmcnt(0)
	v_mov_b32_e32 v128, v152
	s_waitcnt vmcnt(0)
	s_barrier
	v_ashrrev_i32_e32 v129, 6, v128
	v_lshrrev_b32_e32 v131, 3, v128
	v_mul_lo_u32 v130, v129, s17
	v_and_b32_e32 v131, 4, v131
	v_lshlrev_b32_e32 v132, 1, v128
	v_add_u32_e32 v130, 16, v130
	v_and_b32_e32 v132, 62, v132
	v_mul_u32_u24_e32 v131, 0x110, v131
	v_add3_u32 v131, v130, v132, v131
	v_and_b32_e32 v194, 1, v152
	v_mov_b32_e32 v193, 0x01000504
	v_mov_b32_e32 v195, 0x07060302
	v_cmp_eq_u32_e32 vcc, 1, v194
	v_mul_u32_u24_e32 v194, 0x10e, v194
	v_add_u32_e32 v192, v131, v194
	v_cndmask_b32_e32 v193, v193, v195, vcc
	v_cvt_pk_bf16_f32 v194, v112, v113
	v_cvt_pk_bf16_f32 v195, v96, v97
	v_cvt_pk_bf16_f32 v196, v80, v81
	v_cvt_pk_bf16_f32 v197, v64, v65
	v_mov_b32_dpp v198, v194 quad_perm:[1,0,3,2] row_mask:0xf bank_mask:0xf
	v_mov_b32_dpp v199, v195 quad_perm:[1,0,3,2] row_mask:0xf bank_mask:0xf
	v_mov_b32_dpp v200, v196 quad_perm:[1,0,3,2] row_mask:0xf bank_mask:0xf
	v_mov_b32_dpp v201, v197 quad_perm:[1,0,3,2] row_mask:0xf bank_mask:0xf
	v_perm_b32 v202, v194, v198, v193
	v_perm_b32 v203, v195, v199, v193
	v_perm_b32 v206, v196, v200, v193
	v_perm_b32 v207, v197, v201, v193
	ds_write_b32 v192, v202 offset:0
	ds_write_b32 v192, v203 offset:64
	ds_write_b32 v192, v206 offset:128
	ds_write_b32 v192, v207 offset:192
	v_cvt_pk_bf16_f32 v194, v114, v115
	v_cvt_pk_bf16_f32 v195, v98, v99
	v_cvt_pk_bf16_f32 v196, v82, v83
	v_cvt_pk_bf16_f32 v197, v66, v67
	v_mov_b32_dpp v198, v194 quad_perm:[1,0,3,2] row_mask:0xf bank_mask:0xf
	v_mov_b32_dpp v199, v195 quad_perm:[1,0,3,2] row_mask:0xf bank_mask:0xf
	v_mov_b32_dpp v200, v196 quad_perm:[1,0,3,2] row_mask:0xf bank_mask:0xf
	v_mov_b32_dpp v201, v197 quad_perm:[1,0,3,2] row_mask:0xf bank_mask:0xf
	v_perm_b32 v202, v194, v198, v193
	v_perm_b32 v203, v195, v199, v193
	v_perm_b32 v206, v196, v200, v193
	v_perm_b32 v207, v197, v201, v193
	ds_write_b32 v192, v202 offset:544
	ds_write_b32 v192, v203 offset:608
	ds_write_b32 v192, v206 offset:672
	ds_write_b32 v192, v207 offset:736
	v_cvt_pk_bf16_f32 v194, v116, v117
	v_cvt_pk_bf16_f32 v195, v100, v101
	v_cvt_pk_bf16_f32 v196, v84, v85
	v_cvt_pk_bf16_f32 v197, v68, v69
	v_mov_b32_dpp v198, v194 quad_perm:[1,0,3,2] row_mask:0xf bank_mask:0xf
	v_mov_b32_dpp v199, v195 quad_perm:[1,0,3,2] row_mask:0xf bank_mask:0xf
	v_mov_b32_dpp v200, v196 quad_perm:[1,0,3,2] row_mask:0xf bank_mask:0xf
	v_mov_b32_dpp v201, v197 quad_perm:[1,0,3,2] row_mask:0xf bank_mask:0xf
	v_perm_b32 v202, v194, v198, v193
	v_perm_b32 v203, v195, v199, v193
	v_perm_b32 v206, v196, v200, v193
	v_perm_b32 v207, v197, v201, v193
	ds_write_b32 v192, v202 offset:2176
	ds_write_b32 v192, v203 offset:2240
	ds_write_b32 v192, v206 offset:2304
	ds_write_b32 v192, v207 offset:2368
	v_cvt_pk_bf16_f32 v194, v118, v119
	v_cvt_pk_bf16_f32 v195, v102, v103
	v_cvt_pk_bf16_f32 v196, v86, v87
	v_cvt_pk_bf16_f32 v197, v70, v71
	v_mov_b32_dpp v198, v194 quad_perm:[1,0,3,2] row_mask:0xf bank_mask:0xf
	v_mov_b32_dpp v199, v195 quad_perm:[1,0,3,2] row_mask:0xf bank_mask:0xf
	v_mov_b32_dpp v200, v196 quad_perm:[1,0,3,2] row_mask:0xf bank_mask:0xf
	v_mov_b32_dpp v201, v197 quad_perm:[1,0,3,2] row_mask:0xf bank_mask:0xf
	v_perm_b32 v202, v194, v198, v193
	v_perm_b32 v203, v195, v199, v193
	v_perm_b32 v206, v196, v200, v193
	v_perm_b32 v207, v197, v201, v193
	ds_write_b32 v192, v202 offset:2720
	ds_write_b32 v192, v203 offset:2784
	ds_write_b32 v192, v206 offset:2848
	ds_write_b32 v192, v207 offset:2912
	v_cvt_pk_bf16_f32 v194, v120, v121
	v_cvt_pk_bf16_f32 v195, v104, v105
	v_cvt_pk_bf16_f32 v196, v88, v89
	v_cvt_pk_bf16_f32 v197, v72, v73
	v_mov_b32_dpp v198, v194 quad_perm:[1,0,3,2] row_mask:0xf bank_mask:0xf
	v_mov_b32_dpp v199, v195 quad_perm:[1,0,3,2] row_mask:0xf bank_mask:0xf
	v_mov_b32_dpp v200, v196 quad_perm:[1,0,3,2] row_mask:0xf bank_mask:0xf
	v_mov_b32_dpp v201, v197 quad_perm:[1,0,3,2] row_mask:0xf bank_mask:0xf
	v_perm_b32 v202, v194, v198, v193
	v_perm_b32 v203, v195, v199, v193
	v_perm_b32 v206, v196, v200, v193
	v_perm_b32 v207, v197, v201, v193
	ds_write_b32 v192, v202 offset:4352
	ds_write_b32 v192, v203 offset:4416
	ds_write_b32 v192, v206 offset:4480
	ds_write_b32 v192, v207 offset:4544
	v_cvt_pk_bf16_f32 v194, v122, v123
	v_cvt_pk_bf16_f32 v195, v106, v107
	v_cvt_pk_bf16_f32 v196, v90, v91
	v_cvt_pk_bf16_f32 v197, v74, v75
	v_mov_b32_dpp v198, v194 quad_perm:[1,0,3,2] row_mask:0xf bank_mask:0xf
	v_mov_b32_dpp v199, v195 quad_perm:[1,0,3,2] row_mask:0xf bank_mask:0xf
	v_mov_b32_dpp v200, v196 quad_perm:[1,0,3,2] row_mask:0xf bank_mask:0xf
	v_mov_b32_dpp v201, v197 quad_perm:[1,0,3,2] row_mask:0xf bank_mask:0xf
	v_perm_b32 v202, v194, v198, v193
	v_perm_b32 v203, v195, v199, v193
	v_perm_b32 v206, v196, v200, v193
	v_perm_b32 v207, v197, v201, v193
	ds_write_b32 v192, v202 offset:4896
	ds_write_b32 v192, v203 offset:4960
	ds_write_b32 v192, v206 offset:5024
	ds_write_b32 v192, v207 offset:5088
	v_cvt_pk_bf16_f32 v194, v124, v125
	v_cvt_pk_bf16_f32 v195, v108, v109
	v_cvt_pk_bf16_f32 v196, v92, v93
	v_cvt_pk_bf16_f32 v197, v76, v77
	v_mov_b32_dpp v198, v194 quad_perm:[1,0,3,2] row_mask:0xf bank_mask:0xf
	v_mov_b32_dpp v199, v195 quad_perm:[1,0,3,2] row_mask:0xf bank_mask:0xf
	v_mov_b32_dpp v200, v196 quad_perm:[1,0,3,2] row_mask:0xf bank_mask:0xf
	v_mov_b32_dpp v201, v197 quad_perm:[1,0,3,2] row_mask:0xf bank_mask:0xf
	v_perm_b32 v202, v194, v198, v193
	v_perm_b32 v203, v195, v199, v193
	v_perm_b32 v206, v196, v200, v193
	v_perm_b32 v207, v197, v201, v193
	ds_write_b32 v192, v202 offset:6528
	ds_write_b32 v192, v203 offset:6592
	ds_write_b32 v192, v206 offset:6656
	ds_write_b32 v192, v207 offset:6720
; __device__ __forceinline__ void gemm_nt_phase(const u16* A, int lda, const u16* Bt, int ldb, u16* C, int ldc,
;                               int Mt, int Nt, int K, int qcols, float qscale, u16* smem,
;                               u16* vtx = nullptr, u16* vtc = nullptr, u16* smv = nullptr) {
;     ...
;       char* wb = reinterpret_cast<char*>(smem) + wid * 17408;
; #pragma unroll
;       for (int i = 0; i < 2; ++i)
; #pragma unroll
;         for (int j = 0; j < 4; ++j)
; #pragma unroll
;           for (int r = 0; r < 16; ++r) {
;             const int row = i * 32 + (r & 3) + 8 * (r >> 2) + 4 * (lane >> 5);
;             const int col = j * 32 + (lane & 31);
;             *reinterpret_cast<u16*>(wb + row * 272 + col * 2) = f2bf(acc[i][j][r] * sc);
;           }
;       asm volatile("s_waitcnt lgkmcnt(0)" ::: "memory");
	v_cvt_pk_bf16_f32 v194, v126, v127
	v_cvt_pk_bf16_f32 v195, v110, v111
	v_cvt_pk_bf16_f32 v196, v94, v95
	v_cvt_pk_bf16_f32 v197, v78, v79
	v_mov_b32_dpp v198, v194 quad_perm:[1,0,3,2] row_mask:0xf bank_mask:0xf
	v_mov_b32_dpp v199, v195 quad_perm:[1,0,3,2] row_mask:0xf bank_mask:0xf
	v_mov_b32_dpp v200, v196 quad_perm:[1,0,3,2] row_mask:0xf bank_mask:0xf
	v_mov_b32_dpp v201, v197 quad_perm:[1,0,3,2] row_mask:0xf bank_mask:0xf
	v_perm_b32 v202, v194, v198, v193
	v_perm_b32 v203, v195, v199, v193
	v_perm_b32 v206, v196, v200, v193
	v_perm_b32 v207, v197, v201, v193
	ds_write_b32 v192, v202 offset:7072
	ds_write_b32 v192, v203 offset:7136
	ds_write_b32 v192, v206 offset:7200
	ds_write_b32 v192, v207 offset:7264
	v_cvt_pk_bf16_f32 v194, v48, v49
	v_cvt_pk_bf16_f32 v195, v32, v33
	v_cvt_pk_bf16_f32 v196, v16, v17
	v_cvt_pk_bf16_f32 v197, v0, v1
	v_mov_b32_dpp v198, v194 quad_perm:[1,0,3,2] row_mask:0xf bank_mask:0xf
	v_mov_b32_dpp v199, v195 quad_perm:[1,0,3,2] row_mask:0xf bank_mask:0xf
	v_mov_b32_dpp v200, v196 quad_perm:[1,0,3,2] row_mask:0xf bank_mask:0xf
	v_mov_b32_dpp v201, v197 quad_perm:[1,0,3,2] row_mask:0xf bank_mask:0xf
	v_perm_b32 v202, v194, v198, v193
	v_perm_b32 v203, v195, v199, v193
	v_perm_b32 v206, v196, v200, v193
	v_perm_b32 v207, v197, v201, v193
	ds_write_b32 v192, v202 offset:8704
	ds_write_b32 v192, v203 offset:8768
	ds_write_b32 v192, v206 offset:8832
	ds_write_b32 v192, v207 offset:8896
	v_cvt_pk_bf16_f32 v194, v50, v51
	v_cvt_pk_bf16_f32 v195, v34, v35
	v_cvt_pk_bf16_f32 v196, v18, v19
	v_cvt_pk_bf16_f32 v197, v2, v3
	v_mov_b32_dpp v198, v194 quad_perm:[1,0,3,2] row_mask:0xf bank_mask:0xf
	v_mov_b32_dpp v199, v195 quad_perm:[1,0,3,2] row_mask:0xf bank_mask:0xf
	v_mov_b32_dpp v200, v196 quad_perm:[1,0,3,2] row_mask:0xf bank_mask:0xf
	v_mov_b32_dpp v201, v197 quad_perm:[1,0,3,2] row_mask:0xf bank_mask:0xf
	v_perm_b32 v202, v194, v198, v193
	v_perm_b32 v203, v195, v199, v193
	v_perm_b32 v206, v196, v200, v193
	v_perm_b32 v207, v197, v201, v193
	ds_write_b32 v192, v202 offset:9248
	ds_write_b32 v192, v203 offset:9312
	ds_write_b32 v192, v206 offset:9376
	ds_write_b32 v192, v207 offset:9440
	v_cvt_pk_bf16_f32 v194, v52, v53
	v_cvt_pk_bf16_f32 v195, v36, v37
	v_cvt_pk_bf16_f32 v196, v20, v21
	v_cvt_pk_bf16_f32 v197, v4, v5
	v_mov_b32_dpp v198, v194 quad_perm:[1,0,3,2] row_mask:0xf bank_mask:0xf
	v_mov_b32_dpp v199, v195 quad_perm:[1,0,3,2] row_mask:0xf bank_mask:0xf
	v_mov_b32_dpp v200, v196 quad_perm:[1,0,3,2] row_mask:0xf bank_mask:0xf
	v_mov_b32_dpp v201, v197 quad_perm:[1,0,3,2] row_mask:0xf bank_mask:0xf
	v_perm_b32 v202, v194, v198, v193
	v_perm_b32 v203, v195, v199, v193
	v_perm_b32 v206, v196, v200, v193
	v_perm_b32 v207, v197, v201, v193
	ds_write_b32 v192, v202 offset:10880
	ds_write_b32 v192, v203 offset:10944
	ds_write_b32 v192, v206 offset:11008
	ds_write_b32 v192, v207 offset:11072
	v_cvt_pk_bf16_f32 v194, v54, v55
	v_cvt_pk_bf16_f32 v195, v38, v39
	v_cvt_pk_bf16_f32 v196, v22, v23
	v_cvt_pk_bf16_f32 v197, v6, v7
	v_mov_b32_dpp v198, v194 quad_perm:[1,0,3,2] row_mask:0xf bank_mask:0xf
	v_mov_b32_dpp v199, v195 quad_perm:[1,0,3,2] row_mask:0xf bank_mask:0xf
	v_mov_b32_dpp v200, v196 quad_perm:[1,0,3,2] row_mask:0xf bank_mask:0xf
	v_mov_b32_dpp v201, v197 quad_perm:[1,0,3,2] row_mask:0xf bank_mask:0xf
	v_perm_b32 v202, v194, v198, v193
	v_perm_b32 v203, v195, v199, v193
	v_perm_b32 v206, v196, v200, v193
	v_perm_b32 v207, v197, v201, v193
	ds_write_b32 v192, v202 offset:11424
	ds_write_b32 v192, v203 offset:11488
	ds_write_b32 v192, v206 offset:11552
	ds_write_b32 v192, v207 offset:11616
	v_cvt_pk_bf16_f32 v194, v56, v57
	v_cvt_pk_bf16_f32 v195, v40, v41
	v_cvt_pk_bf16_f32 v196, v24, v25
	v_cvt_pk_bf16_f32 v197, v8, v9
	v_mov_b32_dpp v198, v194 quad_perm:[1,0,3,2] row_mask:0xf bank_mask:0xf
	v_mov_b32_dpp v199, v195 quad_perm:[1,0,3,2] row_mask:0xf bank_mask:0xf
	v_mov_b32_dpp v200, v196 quad_perm:[1,0,3,2] row_mask:0xf bank_mask:0xf
	v_mov_b32_dpp v201, v197 quad_perm:[1,0,3,2] row_mask:0xf bank_mask:0xf
	v_perm_b32 v202, v194, v198, v193
	v_perm_b32 v203, v195, v199, v193
	v_perm_b32 v206, v196, v200, v193
	v_perm_b32 v207, v197, v201, v193
	ds_write_b32 v192, v202 offset:13056
	ds_write_b32 v192, v203 offset:13120
	ds_write_b32 v192, v206 offset:13184
	ds_write_b32 v192, v207 offset:13248
	v_cvt_pk_bf16_f32 v194, v58, v59
	v_cvt_pk_bf16_f32 v195, v42, v43
	v_cvt_pk_bf16_f32 v196, v26, v27
	v_cvt_pk_bf16_f32 v197, v10, v11
	v_mov_b32_dpp v198, v194 quad_perm:[1,0,3,2] row_mask:0xf bank_mask:0xf
	v_mov_b32_dpp v199, v195 quad_perm:[1,0,3,2] row_mask:0xf bank_mask:0xf
	v_mov_b32_dpp v200, v196 quad_perm:[1,0,3,2] row_mask:0xf bank_mask:0xf
	v_mov_b32_dpp v201, v197 quad_perm:[1,0,3,2] row_mask:0xf bank_mask:0xf
	v_perm_b32 v202, v194, v198, v193
	v_perm_b32 v203, v195, v199, v193
	v_perm_b32 v206, v196, v200, v193
	v_perm_b32 v207, v197, v201, v193
	ds_write_b32 v192, v202 offset:13600
	ds_write_b32 v192, v203 offset:13664
	ds_write_b32 v192, v206 offset:13728
	ds_write_b32 v192, v207 offset:13792
	v_cvt_pk_bf16_f32 v194, v60, v61
	v_cvt_pk_bf16_f32 v195, v44, v45
	v_cvt_pk_bf16_f32 v196, v28, v29
	v_cvt_pk_bf16_f32 v197, v12, v13
	v_mov_b32_dpp v198, v194 quad_perm:[1,0,3,2] row_mask:0xf bank_mask:0xf
	v_mov_b32_dpp v199, v195 quad_perm:[1,0,3,2] row_mask:0xf bank_mask:0xf
	v_mov_b32_dpp v200, v196 quad_perm:[1,0,3,2] row_mask:0xf bank_mask:0xf
	v_mov_b32_dpp v201, v197 quad_perm:[1,0,3,2] row_mask:0xf bank_mask:0xf
	v_perm_b32 v202, v194, v198, v193
	v_perm_b32 v203, v195, v199, v193
	v_perm_b32 v206, v196, v200, v193
	v_perm_b32 v207, v197, v201, v193
	ds_write_b32 v192, v202 offset:15232
	ds_write_b32 v192, v203 offset:15296
	ds_write_b32 v192, v206 offset:15360
	ds_write_b32 v192, v207 offset:15424
	v_cvt_pk_bf16_f32 v194, v62, v63
	v_cvt_pk_bf16_f32 v195, v46, v47
	v_cvt_pk_bf16_f32 v196, v30, v31
	v_cvt_pk_bf16_f32 v197, v14, v15
	v_mov_b32_dpp v198, v194 quad_perm:[1,0,3,2] row_mask:0xf bank_mask:0xf
	v_mov_b32_dpp v199, v195 quad_perm:[1,0,3,2] row_mask:0xf bank_mask:0xf
	v_mov_b32_dpp v200, v196 quad_perm:[1,0,3,2] row_mask:0xf bank_mask:0xf
	v_mov_b32_dpp v201, v197 quad_perm:[1,0,3,2] row_mask:0xf bank_mask:0xf
	v_perm_b32 v202, v194, v198, v193
	v_perm_b32 v203, v195, v199, v193
	v_perm_b32 v206, v196, v200, v193
	v_perm_b32 v207, v197, v201, v193
	ds_write_b32 v192, v202 offset:15776
	ds_write_b32 v192, v203 offset:15840
	ds_write_b32 v192, v206 offset:15904
	ds_write_b32 v192, v207 offset:15968
	v_and_b32_e32 v0, 15, v128
	v_bfe_u32 v7, v128, 4, 2
	s_lshl_b32 s6, s6, 8
	s_lshl_b64 s[8:9], s[8:9], 1
	v_lshlrev_b32_e32 v1, 4, v0
	v_lshlrev_b32_e32 v6, 3, v0
	v_mul_u32_u24_e32 v0, 0x110, v7
	s_add_u32 s8, s88, s8
	s_waitcnt lgkmcnt(0)
; __device__ __forceinline__ void gemm_nt_phase(const u16* A, int lda, const u16* Bt, int ldb, u16* C, int ldc,
;                               int Mt, int Nt, int K, int qcols, float qscale, u16* smem,
;                               u16* vtx = nullptr, u16* vtc = nullptr, u16* smv = nullptr) {
;     ...
;       asm volatile("s_waitcnt lgkmcnt(0)" ::: "memory");
; #pragma unroll
;       for (int q = 0; q < 16; ++q) {
;         const int idx = q * 64 + lane, row = idx >> 4, c16 = idx & 15;
;         const uint4 v = *reinterpret_cast<const uint4*>(wb + row * 272 + c16 * 16);
;         *reinterpret_cast<uint4*>(&Cb[(unsigned)((wm * 64 + row) * ldc + wn * 128 + c16 * 8)]) = v;
;       }
;     }
;     __syncthreads();
	v_lshrrev_b32_e32 v4, 1, v128
	v_lshlrev_b32_e32 v2, 7, v129
	v_add3_u32 v10, v130, v1, v0
	s_addc_u32 s9, s89, s9
	s_ashr_i32 s7, s6, 31
	v_and_b32_e32 v5, 0x80, v2
	ds_read_b128 v[0:3], v10
	v_and_or_b32 v4, v4, s18, v7
	s_lshl_b64 s[6:7], s[6:7], 1
	v_lshlrev_b32_e32 v4, 10, v4
	s_add_u32 s6, s8, s6
	v_or3_b32 v154, v5, v6, v4
	ds_read_b128 v[4:7], v10 offset:1088
	s_addc_u32 s7, s9, s7
	v_lshl_add_u64 v[8:9], v[154:155], 1, s[6:7]
	s_waitcnt lgkmcnt(1)
	global_store_dwordx4 v[8:9], v[0:3], off
	s_add_i32 s19, s19, s96
	s_cmp_lt_i32 s19, s3
	v_or_b32_e32 v0, 0x1000, v154
	v_mov_b32_e32 v1, v155
	v_lshl_add_u64 v[0:1], v[0:1], 1, s[6:7]
	s_waitcnt lgkmcnt(0)
	global_store_dwordx4 v[0:1], v[4:7], off
	ds_read_b128 v[0:3], v10 offset:2176
	s_nop 0
	v_or_b32_e32 v4, 0x2000, v154
	v_mov_b32_e32 v5, v155
	v_lshl_add_u64 v[8:9], v[4:5], 1, s[6:7]
	ds_read_b128 v[4:7], v10 offset:3264
	s_waitcnt lgkmcnt(1)
	global_store_dwordx4 v[8:9], v[0:3], off
	s_nop 1
	v_or_b32_e32 v0, 0x3000, v154
	v_mov_b32_e32 v1, v155
	v_lshl_add_u64 v[0:1], v[0:1], 1, s[6:7]
	s_waitcnt lgkmcnt(0)
	global_store_dwordx4 v[0:1], v[4:7], off
	ds_read_b128 v[0:3], v10 offset:4352
	s_nop 0
	v_or_b32_e32 v4, 0x4000, v154
	v_mov_b32_e32 v5, v155
	v_lshl_add_u64 v[8:9], v[4:5], 1, s[6:7]
	ds_read_b128 v[4:7], v10 offset:5440
	s_waitcnt lgkmcnt(1)
	global_store_dwordx4 v[8:9], v[0:3], off
	s_nop 1
	v_or_b32_e32 v0, 0x5000, v154
	v_mov_b32_e32 v1, v155
	v_lshl_add_u64 v[0:1], v[0:1], 1, s[6:7]
	s_waitcnt lgkmcnt(0)
	global_store_dwordx4 v[0:1], v[4:7], off
	ds_read_b128 v[0:3], v10 offset:6528
	s_nop 0
	v_or_b32_e32 v4, 0x6000, v154
	v_mov_b32_e32 v5, v155
	v_lshl_add_u64 v[8:9], v[4:5], 1, s[6:7]
	ds_read_b128 v[4:7], v10 offset:7616
	s_waitcnt lgkmcnt(1)
	global_store_dwordx4 v[8:9], v[0:3], off
	s_nop 1
	v_or_b32_e32 v0, 0x7000, v154
	v_mov_b32_e32 v1, v155
	v_lshl_add_u64 v[0:1], v[0:1], 1, s[6:7]
	s_waitcnt lgkmcnt(0)
	global_store_dwordx4 v[0:1], v[4:7], off
	ds_read_b128 v[0:3], v10 offset:8704
	s_nop 0
	v_or_b32_e32 v4, 0x8000, v154
	v_mov_b32_e32 v5, v155
	v_lshl_add_u64 v[8:9], v[4:5], 1, s[6:7]
	ds_read_b128 v[4:7], v10 offset:9792
	s_waitcnt lgkmcnt(1)
	global_store_dwordx4 v[8:9], v[0:3], off
	s_nop 1
	v_or_b32_e32 v0, 0x9000, v154
	v_mov_b32_e32 v1, v155
	v_lshl_add_u64 v[0:1], v[0:1], 1, s[6:7]
	s_waitcnt lgkmcnt(0)
	global_store_dwordx4 v[0:1], v[4:7], off
	ds_read_b128 v[0:3], v10 offset:10880
	s_nop 0
	v_or_b32_e32 v4, 0xa000, v154
	v_mov_b32_e32 v5, v155
	v_lshl_add_u64 v[8:9], v[4:5], 1, s[6:7]
	ds_read_b128 v[4:7], v10 offset:11968
	s_waitcnt lgkmcnt(1)
	global_store_dwordx4 v[8:9], v[0:3], off
	s_nop 1
	v_or_b32_e32 v0, 0xb000, v154
	v_mov_b32_e32 v1, v155
	v_lshl_add_u64 v[0:1], v[0:1], 1, s[6:7]
	s_waitcnt lgkmcnt(0)
	global_store_dwordx4 v[0:1], v[4:7], off
	ds_read_b128 v[0:3], v10 offset:13056
	s_nop 0
	v_or_b32_e32 v4, 0xc000, v154
	v_mov_b32_e32 v5, v155
	v_lshl_add_u64 v[8:9], v[4:5], 1, s[6:7]
	ds_read_b128 v[4:7], v10 offset:14144
	s_waitcnt lgkmcnt(1)
	global_store_dwordx4 v[8:9], v[0:3], off
	v_or_b32_e32 v8, 0xe000, v154
	v_mov_b32_e32 v9, v155
	v_or_b32_e32 v0, 0xd000, v154
	v_mov_b32_e32 v1, v155
	v_lshl_add_u64 v[0:1], v[0:1], 1, s[6:7]
	s_waitcnt lgkmcnt(0)
	global_store_dwordx4 v[0:1], v[4:7], off
	ds_read_b128 v[0:3], v10 offset:15232
	ds_read_b128 v[4:7], v10 offset:16320
	v_lshl_add_u64 v[8:9], v[8:9], 1, s[6:7]
	v_or_b32_e32 v154, 0xf000, v154
	s_waitcnt lgkmcnt(1)
	global_store_dwordx4 v[8:9], v[0:3], off
	s_nop 1
	v_lshl_add_u64 v[0:1], v[154:155], 1, s[6:7]
	s_waitcnt lgkmcnt(0)
	global_store_dwordx4 v[0:1], v[4:7], off
	s_barrier
	s_cbranch_scc0 .LBB0_867

; __device__ __forceinline__ void gemm_nt_phase(const u16* A, int lda, const u16* Bt, int ldb, u16* C, int ldc,
;                               int Mt, int Nt, int K, int qcols, float qscale, u16* smem,
;                               u16* vtx = nullptr, u16* vtc = nullptr, u16* smv = nullptr) {
;     ...
;     int tid_ = threadIdx.x;
;     asm volatile("" : "+v"(tid_));
;     const int lane = tid_ & 63, wid = tid_ >> 6, wm = wid >> 1, wn = wid & 1;
;     if (vtx != nullptr && nt >= 8) {
;       u16* dst; unsigned tstride;
;       if (mt < 128) { dst = vtx + (long)(mt >> 5) * 1024 * 8192 + (mt & 31) * 256; tstride = 8192; }
;       else          { dst = vtc + (long)(mt - 128) * 1024 * 256; tstride = 256; }
; #pragma unroll
;       for (int i = 0; i < 2; ++i)
; #pragma unroll
;         for (int j = 0; j < 4; ++j)
; #pragma unroll
;           for (int rq = 0; rq < 4; ++rq) {
;             const int row = wm * 64 + i * 32 + 8 * rq + 4 * (lane >> 5);
;             const int hd = (nt - 8) * 256 + wn * 128 + j * 32 + (lane & 31);
;             const unsigned v0 = f2bf(acc[i][j][4 * rq + 0]), v1 = f2bf(acc[i][j][4 * rq + 1]);
;             const unsigned v2 = f2bf(acc[i][j][4 * rq + 2]), v3 = f2bf(acc[i][j][4 * rq + 3]);
;             *reinterpret_cast<uint2*>(&dst[(unsigned)(hd * tstride + row)]) = make_uint2(v0 | (v1 << 16), v2 | (v3 << 16));
;           }
;     } else {
;       char* wb = reinterpret_cast<char*>(smem) + wid * 17408;
; #pragma unroll
;       for (int i = 0; i < 2; ++i)
; #pragma unroll
;         for (int j = 0; j < 4; ++j)
; #pragma unroll
;           for (int r = 0; r < 16; ++r) {
;             const int row = i * 32 + (r & 3) + 8 * (r >> 2) + 4 * (lane >> 5);
;             const int col = j * 32 + (lane & 31);
;             *reinterpret_cast<u16*>(wb + row * 272 + col * 2) = f2bf(acc[i][j][r] * sc);
;           }
.LBB0_1144:
	s_waitcnt lgkmcnt(0)
	v_mov_b32_e32 v128, v152
	s_waitcnt vmcnt(0)
	s_barrier
	v_ashrrev_i32_e32 v129, 6, v128
	v_lshrrev_b32_e32 v131, 3, v128
	v_mul_lo_u32 v130, v129, s15
	v_and_b32_e32 v131, 4, v131
	v_lshlrev_b32_e32 v132, 1, v128
	v_add_u32_e32 v130, 16, v130
	v_and_b32_e32 v132, 62, v132
	v_mul_u32_u24_e32 v131, 0x110, v131
	v_add3_u32 v131, v130, v132, v131
	v_and_b32_e32 v194, 1, v152
	v_mov_b32_e32 v193, 0x01000504
	v_mov_b32_e32 v195, 0x07060302
	v_cmp_eq_u32_e32 vcc, 1, v194
	v_mul_u32_u24_e32 v194, 0x10e, v194
	v_add_u32_e32 v192, v131, v194
	v_cndmask_b32_e32 v193, v193, v195, vcc
	v_cvt_pk_bf16_f32 v194, v112, v113
	v_cvt_pk_bf16_f32 v195, v96, v97
	v_cvt_pk_bf16_f32 v196, v80, v81
	v_cvt_pk_bf16_f32 v197, v64, v65
	v_mov_b32_dpp v198, v194 quad_perm:[1,0,3,2] row_mask:0xf bank_mask:0xf
	v_mov_b32_dpp v199, v195 quad_perm:[1,0,3,2] row_mask:0xf bank_mask:0xf
	v_mov_b32_dpp v200, v196 quad_perm:[1,0,3,2] row_mask:0xf bank_mask:0xf
	v_mov_b32_dpp v201, v197 quad_perm:[1,0,3,2] row_mask:0xf bank_mask:0xf
	v_perm_b32 v202, v194, v198, v193
	v_perm_b32 v203, v195, v199, v193
	v_perm_b32 v206, v196, v200, v193
	v_perm_b32 v207, v197, v201, v193
	ds_write_b32 v192, v202 offset:0
	ds_write_b32 v192, v203 offset:64
	ds_write_b32 v192, v206 offset:128
	ds_write_b32 v192, v207 offset:192
	v_cvt_pk_bf16_f32 v194, v114, v115
	v_cvt_pk_bf16_f32 v195, v98, v99
	v_cvt_pk_bf16_f32 v196, v82, v83
	v_cvt_pk_bf16_f32 v197, v66, v67
	v_mov_b32_dpp v198, v194 quad_perm:[1,0,3,2] row_mask:0xf bank_mask:0xf
	v_mov_b32_dpp v199, v195 quad_perm:[1,0,3,2] row_mask:0xf bank_mask:0xf
	v_mov_b32_dpp v200, v196 quad_perm:[1,0,3,2] row_mask:0xf bank_mask:0xf
	v_mov_b32_dpp v201, v197 quad_perm:[1,0,3,2] row_mask:0xf bank_mask:0xf
	v_perm_b32 v202, v194, v198, v193
	v_perm_b32 v203, v195, v199, v193
	v_perm_b32 v206, v196, v200, v193
	v_perm_b32 v207, v197, v201, v193
	ds_write_b32 v192, v202 offset:544
	ds_write_b32 v192, v203 offset:608
	ds_write_b32 v192, v206 offset:672
	ds_write_b32 v192, v207 offset:736
	v_cvt_pk_bf16_f32 v194, v116, v117
	v_cvt_pk_bf16_f32 v195, v100, v101
	v_cvt_pk_bf16_f32 v196, v84, v85
	v_cvt_pk_bf16_f32 v197, v68, v69
	v_mov_b32_dpp v198, v194 quad_perm:[1,0,3,2] row_mask:0xf bank_mask:0xf
	v_mov_b32_dpp v199, v195 quad_perm:[1,0,3,2] row_mask:0xf bank_mask:0xf
	v_mov_b32_dpp v200, v196 quad_perm:[1,0,3,2] row_mask:0xf bank_mask:0xf
	v_mov_b32_dpp v201, v197 quad_perm:[1,0,3,2] row_mask:0xf bank_mask:0xf
	v_perm_b32 v202, v194, v198, v193
	v_perm_b32 v203, v195, v199, v193
	v_perm_b32 v206, v196, v200, v193
	v_perm_b32 v207, v197, v201, v193
	ds_write_b32 v192, v202 offset:2176
	ds_write_b32 v192, v203 offset:2240
	ds_write_b32 v192, v206 offset:2304
	ds_write_b32 v192, v207 offset:2368
	v_cvt_pk_bf16_f32 v194, v118, v119
	v_cvt_pk_bf16_f32 v195, v102, v103
	v_cvt_pk_bf16_f32 v196, v86, v87
	v_cvt_pk_bf16_f32 v197, v70, v71
	v_mov_b32_dpp v198, v194 quad_perm:[1,0,3,2] row_mask:0xf bank_mask:0xf
	v_mov_b32_dpp v199, v195 quad_perm:[1,0,3,2] row_mask:0xf bank_mask:0xf
	v_mov_b32_dpp v200, v196 quad_perm:[1,0,3,2] row_mask:0xf bank_mask:0xf
	v_mov_b32_dpp v201, v197 quad_perm:[1,0,3,2] row_mask:0xf bank_mask:0xf
	v_perm_b32 v202, v194, v198, v193
	v_perm_b32 v203, v195, v199, v193
	v_perm_b32 v206, v196, v200, v193
	v_perm_b32 v207, v197, v201, v193
	ds_write_b32 v192, v202 offset:2720
	ds_write_b32 v192, v203 offset:2784
	ds_write_b32 v192, v206 offset:2848
	ds_write_b32 v192, v207 offset:2912
	v_cvt_pk_bf16_f32 v194, v120, v121
	v_cvt_pk_bf16_f32 v195, v104, v105
	v_cvt_pk_bf16_f32 v196, v88, v89
	v_cvt_pk_bf16_f32 v197, v72, v73
	v_mov_b32_dpp v198, v194 quad_perm:[1,0,3,2] row_mask:0xf bank_mask:0xf
	v_mov_b32_dpp v199, v195 quad_perm:[1,0,3,2] row_mask:0xf bank_mask:0xf
	v_mov_b32_dpp v200, v196 quad_perm:[1,0,3,2] row_mask:0xf bank_mask:0xf
	v_mov_b32_dpp v201, v197 quad_perm:[1,0,3,2] row_mask:0xf bank_mask:0xf
	v_perm_b32 v202, v194, v198, v193
	v_perm_b32 v203, v195, v199, v193
	v_perm_b32 v206, v196, v200, v193
	v_perm_b32 v207, v197, v201, v193
	ds_write_b32 v192, v202 offset:4352
	ds_write_b32 v192, v203 offset:4416
	ds_write_b32 v192, v206 offset:4480
	ds_write_b32 v192, v207 offset:4544
	v_cvt_pk_bf16_f32 v194, v122, v123
	v_cvt_pk_bf16_f32 v195, v106, v107
	v_cvt_pk_bf16_f32 v196, v90, v91
	v_cvt_pk_bf16_f32 v197, v74, v75
	v_mov_b32_dpp v198, v194 quad_perm:[1,0,3,2] row_mask:0xf bank_mask:0xf
	v_mov_b32_dpp v199, v195 quad_perm:[1,0,3,2] row_mask:0xf bank_mask:0xf
	v_mov_b32_dpp v200, v196 quad_perm:[1,0,3,2] row_mask:0xf bank_mask:0xf
	v_mov_b32_dpp v201, v197 quad_perm:[1,0,3,2] row_mask:0xf bank_mask:0xf
	v_perm_b32 v202, v194, v198, v193
	v_perm_b32 v203, v195, v199, v193
	v_perm_b32 v206, v196, v200, v193
	v_perm_b32 v207, v197, v201, v193
	ds_write_b32 v192, v202 offset:4896
	ds_write_b32 v192, v203 offset:4960
	ds_write_b32 v192, v206 offset:5024
	ds_write_b32 v192, v207 offset:5088
	v_cvt_pk_bf16_f32 v194, v124, v125
	v_cvt_pk_bf16_f32 v195, v108, v109
	v_cvt_pk_bf16_f32 v196, v92, v93
	v_cvt_pk_bf16_f32 v197, v76, v77
	v_mov_b32_dpp v198, v194 quad_perm:[1,0,3,2] row_mask:0xf bank_mask:0xf
	v_mov_b32_dpp v199, v195 quad_perm:[1,0,3,2] row_mask:0xf bank_mask:0xf
	v_mov_b32_dpp v200, v196 quad_perm:[1,0,3,2] row_mask:0xf bank_mask:0xf
	v_mov_b32_dpp v201, v197 quad_perm:[1,0,3,2] row_mask:0xf bank_mask:0xf
	v_perm_b32 v202, v194, v198, v193
	v_perm_b32 v203, v195, v199, v193
	v_perm_b32 v206, v196, v200, v193
	v_perm_b32 v207, v197, v201, v193
	ds_write_b32 v192, v202 offset:6528
	ds_write_b32 v192, v203 offset:6592
	ds_write_b32 v192, v206 offset:6656
	ds_write_b32 v192, v207 offset:6720
; __device__ __forceinline__ void gemm_nt_phase(const u16* A, int lda, const u16* Bt, int ldb, u16* C, int ldc,
;                               int Mt, int Nt, int K, int qcols, float qscale, u16* smem,
;                               u16* vtx = nullptr, u16* vtc = nullptr, u16* smv = nullptr) {
;     ...
;       char* wb = reinterpret_cast<char*>(smem) + wid * 17408;
; #pragma unroll
;       for (int i = 0; i < 2; ++i)
; #pragma unroll
;         for (int j = 0; j < 4; ++j)
; #pragma unroll
;           for (int r = 0; r < 16; ++r) {
;             const int row = i * 32 + (r & 3) + 8 * (r >> 2) + 4 * (lane >> 5);
;             const int col = j * 32 + (lane & 31);
;             *reinterpret_cast<u16*>(wb + row * 272 + col * 2) = f2bf(acc[i][j][r] * sc);
;           }
;       asm volatile("s_waitcnt lgkmcnt(0)" ::: "memory");
	v_cvt_pk_bf16_f32 v194, v126, v127
	v_cvt_pk_bf16_f32 v195, v110, v111
	v_cvt_pk_bf16_f32 v196, v94, v95
	v_cvt_pk_bf16_f32 v197, v78, v79
	v_mov_b32_dpp v198, v194 quad_perm:[1,0,3,2] row_mask:0xf bank_mask:0xf
	v_mov_b32_dpp v199, v195 quad_perm:[1,0,3,2] row_mask:0xf bank_mask:0xf
	v_mov_b32_dpp v200, v196 quad_perm:[1,0,3,2] row_mask:0xf bank_mask:0xf
	v_mov_b32_dpp v201, v197 quad_perm:[1,0,3,2] row_mask:0xf bank_mask:0xf
	v_perm_b32 v202, v194, v198, v193
	v_perm_b32 v203, v195, v199, v193
	v_perm_b32 v206, v196, v200, v193
	v_perm_b32 v207, v197, v201, v193
	ds_write_b32 v192, v202 offset:7072
	ds_write_b32 v192, v203 offset:7136
	ds_write_b32 v192, v206 offset:7200
	ds_write_b32 v192, v207 offset:7264
	v_cvt_pk_bf16_f32 v194, v48, v49
	v_cvt_pk_bf16_f32 v195, v32, v33
	v_cvt_pk_bf16_f32 v196, v16, v17
	v_cvt_pk_bf16_f32 v197, v0, v1
	v_mov_b32_dpp v198, v194 quad_perm:[1,0,3,2] row_mask:0xf bank_mask:0xf
	v_mov_b32_dpp v199, v195 quad_perm:[1,0,3,2] row_mask:0xf bank_mask:0xf
	v_mov_b32_dpp v200, v196 quad_perm:[1,0,3,2] row_mask:0xf bank_mask:0xf
	v_mov_b32_dpp v201, v197 quad_perm:[1,0,3,2] row_mask:0xf bank_mask:0xf
	v_perm_b32 v202, v194, v198, v193
	v_perm_b32 v203, v195, v199, v193
	v_perm_b32 v206, v196, v200, v193
	v_perm_b32 v207, v197, v201, v193
	ds_write_b32 v192, v202 offset:8704
	ds_write_b32 v192, v203 offset:8768
	ds_write_b32 v192, v206 offset:8832
	ds_write_b32 v192, v207 offset:8896
	v_cvt_pk_bf16_f32 v194, v50, v51
	v_cvt_pk_bf16_f32 v195, v34, v35
	v_cvt_pk_bf16_f32 v196, v18, v19
	v_cvt_pk_bf16_f32 v197, v2, v3
	v_mov_b32_dpp v198, v194 quad_perm:[1,0,3,2] row_mask:0xf bank_mask:0xf
	v_mov_b32_dpp v199, v195 quad_perm:[1,0,3,2] row_mask:0xf bank_mask:0xf
	v_mov_b32_dpp v200, v196 quad_perm:[1,0,3,2] row_mask:0xf bank_mask:0xf
	v_mov_b32_dpp v201, v197 quad_perm:[1,0,3,2] row_mask:0xf bank_mask:0xf
	v_perm_b32 v202, v194, v198, v193
	v_perm_b32 v203, v195, v199, v193
	v_perm_b32 v206, v196, v200, v193
	v_perm_b32 v207, v197, v201, v193
	ds_write_b32 v192, v202 offset:9248
	ds_write_b32 v192, v203 offset:9312
	ds_write_b32 v192, v206 offset:9376
	ds_write_b32 v192, v207 offset:9440
	v_cvt_pk_bf16_f32 v194, v52, v53
	v_cvt_pk_bf16_f32 v195, v36, v37
	v_cvt_pk_bf16_f32 v196, v20, v21
	v_cvt_pk_bf16_f32 v197, v4, v5
	v_mov_b32_dpp v198, v194 quad_perm:[1,0,3,2] row_mask:0xf bank_mask:0xf
	v_mov_b32_dpp v199, v195 quad_perm:[1,0,3,2] row_mask:0xf bank_mask:0xf
	v_mov_b32_dpp v200, v196 quad_perm:[1,0,3,2] row_mask:0xf bank_mask:0xf
	v_mov_b32_dpp v201, v197 quad_perm:[1,0,3,2] row_mask:0xf bank_mask:0xf
	v_perm_b32 v202, v194, v198, v193
	v_perm_b32 v203, v195, v199, v193
	v_perm_b32 v206, v196, v200, v193
	v_perm_b32 v207, v197, v201, v193
	ds_write_b32 v192, v202 offset:10880
	ds_write_b32 v192, v203 offset:10944
	ds_write_b32 v192, v206 offset:11008
	ds_write_b32 v192, v207 offset:11072
	v_cvt_pk_bf16_f32 v194, v54, v55
	v_cvt_pk_bf16_f32 v195, v38, v39
	v_cvt_pk_bf16_f32 v196, v22, v23
	v_cvt_pk_bf16_f32 v197, v6, v7
	v_mov_b32_dpp v198, v194 quad_perm:[1,0,3,2] row_mask:0xf bank_mask:0xf
	v_mov_b32_dpp v199, v195 quad_perm:[1,0,3,2] row_mask:0xf bank_mask:0xf
	v_mov_b32_dpp v200, v196 quad_perm:[1,0,3,2] row_mask:0xf bank_mask:0xf
	v_mov_b32_dpp v201, v197 quad_perm:[1,0,3,2] row_mask:0xf bank_mask:0xf
	v_perm_b32 v202, v194, v198, v193
	v_perm_b32 v203, v195, v199, v193
	v_perm_b32 v206, v196, v200, v193
	v_perm_b32 v207, v197, v201, v193
	ds_write_b32 v192, v202 offset:11424
	ds_write_b32 v192, v203 offset:11488
	ds_write_b32 v192, v206 offset:11552
	ds_write_b32 v192, v207 offset:11616
	v_cvt_pk_bf16_f32 v194, v56, v57
	v_cvt_pk_bf16_f32 v195, v40, v41
	v_cvt_pk_bf16_f32 v196, v24, v25
	v_cvt_pk_bf16_f32 v197, v8, v9
	v_mov_b32_dpp v198, v194 quad_perm:[1,0,3,2] row_mask:0xf bank_mask:0xf
	v_mov_b32_dpp v199, v195 quad_perm:[1,0,3,2] row_mask:0xf bank_mask:0xf
	v_mov_b32_dpp v200, v196 quad_perm:[1,0,3,2] row_mask:0xf bank_mask:0xf
	v_mov_b32_dpp v201, v197 quad_perm:[1,0,3,2] row_mask:0xf bank_mask:0xf
	v_perm_b32 v202, v194, v198, v193
	v_perm_b32 v203, v195, v199, v193
	v_perm_b32 v206, v196, v200, v193
	v_perm_b32 v207, v197, v201, v193
	ds_write_b32 v192, v202 offset:13056
	ds_write_b32 v192, v203 offset:13120
	ds_write_b32 v192, v206 offset:13184
	ds_write_b32 v192, v207 offset:13248
	v_cvt_pk_bf16_f32 v194, v58, v59
	v_cvt_pk_bf16_f32 v195, v42, v43
	v_cvt_pk_bf16_f32 v196, v26, v27
	v_cvt_pk_bf16_f32 v197, v10, v11
	v_mov_b32_dpp v198, v194 quad_perm:[1,0,3,2] row_mask:0xf bank_mask:0xf
	v_mov_b32_dpp v199, v195 quad_perm:[1,0,3,2] row_mask:0xf bank_mask:0xf
	v_mov_b32_dpp v200, v196 quad_perm:[1,0,3,2] row_mask:0xf bank_mask:0xf
	v_mov_b32_dpp v201, v197 quad_perm:[1,0,3,2] row_mask:0xf bank_mask:0xf
	v_perm_b32 v202, v194, v198, v193
	v_perm_b32 v203, v195, v199, v193
	v_perm_b32 v206, v196, v200, v193
	v_perm_b32 v207, v197, v201, v193
	ds_write_b32 v192, v202 offset:13600
	ds_write_b32 v192, v203 offset:13664
	ds_write_b32 v192, v206 offset:13728
	ds_write_b32 v192, v207 offset:13792
	v_cvt_pk_bf16_f32 v194, v60, v61
	v_cvt_pk_bf16_f32 v195, v44, v45
	v_cvt_pk_bf16_f32 v196, v28, v29
	v_cvt_pk_bf16_f32 v197, v12, v13
	v_mov_b32_dpp v198, v194 quad_perm:[1,0,3,2] row_mask:0xf bank_mask:0xf
	v_mov_b32_dpp v199, v195 quad_perm:[1,0,3,2] row_mask:0xf bank_mask:0xf
	v_mov_b32_dpp v200, v196 quad_perm:[1,0,3,2] row_mask:0xf bank_mask:0xf
	v_mov_b32_dpp v201, v197 quad_perm:[1,0,3,2] row_mask:0xf bank_mask:0xf
	v_perm_b32 v202, v194, v198, v193
	v_perm_b32 v203, v195, v199, v193
	v_perm_b32 v206, v196, v200, v193
	v_perm_b32 v207, v197, v201, v193
	ds_write_b32 v192, v202 offset:15232
	ds_write_b32 v192, v203 offset:15296
	ds_write_b32 v192, v206 offset:15360
	ds_write_b32 v192, v207 offset:15424
	v_cvt_pk_bf16_f32 v194, v62, v63
	v_cvt_pk_bf16_f32 v195, v46, v47
	v_cvt_pk_bf16_f32 v196, v30, v31
	v_cvt_pk_bf16_f32 v197, v14, v15
	v_mov_b32_dpp v198, v194 quad_perm:[1,0,3,2] row_mask:0xf bank_mask:0xf
	v_mov_b32_dpp v199, v195 quad_perm:[1,0,3,2] row_mask:0xf bank_mask:0xf
	v_mov_b32_dpp v200, v196 quad_perm:[1,0,3,2] row_mask:0xf bank_mask:0xf
	v_mov_b32_dpp v201, v197 quad_perm:[1,0,3,2] row_mask:0xf bank_mask:0xf
	v_perm_b32 v202, v194, v198, v193
	v_perm_b32 v203, v195, v199, v193
	v_perm_b32 v206, v196, v200, v193
	v_perm_b32 v207, v197, v201, v193
	ds_write_b32 v192, v202 offset:15776
	ds_write_b32 v192, v203 offset:15840
	ds_write_b32 v192, v206 offset:15904
	ds_write_b32 v192, v207 offset:15968
	v_and_b32_e32 v0, 15, v128
	v_bfe_u32 v7, v128, 4, 2
	s_lshl_b32 s8, s18, 8
	s_lshl_b64 s[6:7], s[6:7], 19
	v_lshlrev_b32_e32 v1, 4, v0
	v_lshlrev_b32_e32 v6, 3, v0
	v_mul_u32_u24_e32 v0, 0x110, v7
	s_add_u32 s10, s88, s6
	s_waitcnt lgkmcnt(0)
; __device__ __forceinline__ void gemm_nt_phase(const u16* A, int lda, const u16* Bt, int ldb, u16* C, int ldc,
;                               int Mt, int Nt, int K, int qcols, float qscale, u16* smem,
;                               u16* vtx = nullptr, u16* vtc = nullptr, u16* smv = nullptr) {
;     ...
;       asm volatile("s_waitcnt lgkmcnt(0)" ::: "memory");
; #pragma unroll
;       for (int q = 0; q < 16; ++q) {
;         const int idx = q * 64 + lane, row = idx >> 4, c16 = idx & 15;
;         const uint4 v = *reinterpret_cast<const uint4*>(wb + row * 272 + c16 * 16);
;         *reinterpret_cast<uint4*>(&Cb[(unsigned)((wm * 64 + row) * ldc + wn * 128 + c16 * 8)]) = v;
;       }
;     }
;     __syncthreads();
	v_lshrrev_b32_e32 v4, 1, v128
	v_lshlrev_b32_e32 v2, 7, v129
	v_add3_u32 v10, v130, v1, v0
	s_addc_u32 s11, s89, s7
	s_ashr_i32 s9, s8, 31
	v_and_b32_e32 v5, 0x80, v2
	ds_read_b128 v[0:3], v10
	v_and_or_b32 v4, v4, s16, v7
	s_lshl_b64 s[6:7], s[8:9], 1
	v_lshlrev_b32_e32 v4, 10, v4
	s_add_u32 s6, s10, s6
	v_or3_b32 v154, v5, v6, v4
	ds_read_b128 v[4:7], v10 offset:1088
	s_addc_u32 s7, s11, s7
	v_lshl_add_u64 v[8:9], v[154:155], 1, s[6:7]
	s_waitcnt lgkmcnt(1)
	global_store_dwordx4 v[8:9], v[0:3], off
	s_add_i32 s17, s17, s96
	s_cmp_lt_i32 s17, s3
	v_or_b32_e32 v0, 0x1000, v154
	v_mov_b32_e32 v1, v155
	v_lshl_add_u64 v[0:1], v[0:1], 1, s[6:7]
	s_waitcnt lgkmcnt(0)
	global_store_dwordx4 v[0:1], v[4:7], off
	ds_read_b128 v[0:3], v10 offset:2176
	s_nop 0
	v_or_b32_e32 v4, 0x2000, v154
	v_mov_b32_e32 v5, v155
	v_lshl_add_u64 v[8:9], v[4:5], 1, s[6:7]
	ds_read_b128 v[4:7], v10 offset:3264
	s_waitcnt lgkmcnt(1)
	global_store_dwordx4 v[8:9], v[0:3], off
	s_nop 1
	v_or_b32_e32 v0, 0x3000, v154
	v_mov_b32_e32 v1, v155
	v_lshl_add_u64 v[0:1], v[0:1], 1, s[6:7]
	s_waitcnt lgkmcnt(0)
	global_store_dwordx4 v[0:1], v[4:7], off
	ds_read_b128 v[0:3], v10 offset:4352
	s_nop 0
	v_or_b32_e32 v4, 0x4000, v154
	v_mov_b32_e32 v5, v155
	v_lshl_add_u64 v[8:9], v[4:5], 1, s[6:7]
	ds_read_b128 v[4:7], v10 offset:5440
	s_waitcnt lgkmcnt(1)
	global_store_dwordx4 v[8:9], v[0:3], off
	s_nop 1
	v_or_b32_e32 v0, 0x5000, v154
	v_mov_b32_e32 v1, v155
	v_lshl_add_u64 v[0:1], v[0:1], 1, s[6:7]
	s_waitcnt lgkmcnt(0)
	global_store_dwordx4 v[0:1], v[4:7], off
	ds_read_b128 v[0:3], v10 offset:6528
	s_nop 0
	v_or_b32_e32 v4, 0x6000, v154
	v_mov_b32_e32 v5, v155
	v_lshl_add_u64 v[8:9], v[4:5], 1, s[6:7]
	ds_read_b128 v[4:7], v10 offset:7616
	s_waitcnt lgkmcnt(1)
	global_store_dwordx4 v[8:9], v[0:3], off
	s_nop 1
	v_or_b32_e32 v0, 0x7000, v154
	v_mov_b32_e32 v1, v155
	v_lshl_add_u64 v[0:1], v[0:1], 1, s[6:7]
	s_waitcnt lgkmcnt(0)
	global_store_dwordx4 v[0:1], v[4:7], off
	ds_read_b128 v[0:3], v10 offset:8704
	s_nop 0
	v_or_b32_e32 v4, 0x8000, v154
	v_mov_b32_e32 v5, v155
	v_lshl_add_u64 v[8:9], v[4:5], 1, s[6:7]
	ds_read_b128 v[4:7], v10 offset:9792
	s_waitcnt lgkmcnt(1)
	global_store_dwordx4 v[8:9], v[0:3], off
	s_nop 1
	v_or_b32_e32 v0, 0x9000, v154
	v_mov_b32_e32 v1, v155
	v_lshl_add_u64 v[0:1], v[0:1], 1, s[6:7]
	s_waitcnt lgkmcnt(0)
	global_store_dwordx4 v[0:1], v[4:7], off
	ds_read_b128 v[0:3], v10 offset:10880
	s_nop 0
	v_or_b32_e32 v4, 0xa000, v154
	v_mov_b32_e32 v5, v155
	v_lshl_add_u64 v[8:9], v[4:5], 1, s[6:7]
	ds_read_b128 v[4:7], v10 offset:11968
	s_waitcnt lgkmcnt(1)
	global_store_dwordx4 v[8:9], v[0:3], off
	s_nop 1
	v_or_b32_e32 v0, 0xb000, v154
	v_mov_b32_e32 v1, v155
	v_lshl_add_u64 v[0:1], v[0:1], 1, s[6:7]
	s_waitcnt lgkmcnt(0)
	global_store_dwordx4 v[0:1], v[4:7], off
	ds_read_b128 v[0:3], v10 offset:13056
	s_nop 0
	v_or_b32_e32 v4, 0xc000, v154
	v_mov_b32_e32 v5, v155
	v_lshl_add_u64 v[8:9], v[4:5], 1, s[6:7]
	ds_read_b128 v[4:7], v10 offset:14144
	s_waitcnt lgkmcnt(1)
	global_store_dwordx4 v[8:9], v[0:3], off
	v_or_b32_e32 v8, 0xe000, v154
	v_mov_b32_e32 v9, v155
	v_or_b32_e32 v0, 0xd000, v154
	v_mov_b32_e32 v1, v155
	v_lshl_add_u64 v[0:1], v[0:1], 1, s[6:7]
	s_waitcnt lgkmcnt(0)
	global_store_dwordx4 v[0:1], v[4:7], off
	ds_read_b128 v[0:3], v10 offset:15232
	ds_read_b128 v[4:7], v10 offset:16320
	v_lshl_add_u64 v[8:9], v[8:9], 1, s[6:7]
	v_or_b32_e32 v154, 0xf000, v154
	s_waitcnt lgkmcnt(1)
	global_store_dwordx4 v[8:9], v[0:3], off
	s_nop 1
	v_lshl_add_u64 v[0:1], v[154:155], 1, s[6:7]
	s_waitcnt lgkmcnt(0)
	global_store_dwordx4 v[0:1], v[4:7], off
	s_barrier
	s_cbranch_scc0 .LBB0_1193

; __device__ __forceinline__ void gemm_nt_phase(const u16* A, int lda, const u16* Bt, int ldb, u16* C, int ldc,
;                               int Mt, int Nt, int K, int qcols, float qscale, u16* smem,
;                               u16* vtx = nullptr, u16* vtc = nullptr, u16* smv = nullptr) {
;     ...
;     int tid_ = threadIdx.x;
;     asm volatile("" : "+v"(tid_));
;     const int lane = tid_ & 63, wid = tid_ >> 6, wm = wid >> 1, wn = wid & 1;
;     if (vtx != nullptr && nt >= 8) {
;       u16* dst; unsigned tstride;
;       if (mt < 128) { dst = vtx + (long)(mt >> 5) * 1024 * 8192 + (mt & 31) * 256; tstride = 8192; }
;       else          { dst = vtc + (long)(mt - 128) * 1024 * 256; tstride = 256; }
; #pragma unroll
;       for (int i = 0; i < 2; ++i)
; #pragma unroll
;         for (int j = 0; j < 4; ++j)
; #pragma unroll
;           for (int rq = 0; rq < 4; ++rq) {
;             const int row = wm * 64 + i * 32 + 8 * rq + 4 * (lane >> 5);
;             const int hd = (nt - 8) * 256 + wn * 128 + j * 32 + (lane & 31);
;             const unsigned v0 = f2bf(acc[i][j][4 * rq + 0]), v1 = f2bf(acc[i][j][4 * rq + 1]);
;             const unsigned v2 = f2bf(acc[i][j][4 * rq + 2]), v3 = f2bf(acc[i][j][4 * rq + 3]);
;             *reinterpret_cast<uint2*>(&dst[(unsigned)(hd * tstride + row)]) = make_uint2(v0 | (v1 << 16), v2 | (v3 << 16));
;           }
;     } else {
;       char* wb = reinterpret_cast<char*>(smem) + wid * 17408;
; #pragma unroll
;       for (int i = 0; i < 2; ++i)
; #pragma unroll
;         for (int j = 0; j < 4; ++j)
; #pragma unroll
;           for (int r = 0; r < 16; ++r) {
;             const int row = i * 32 + (r & 3) + 8 * (r >> 2) + 4 * (lane >> 5);
;             const int col = j * 32 + (lane & 31);
;             *reinterpret_cast<u16*>(wb + row * 272 + col * 2) = f2bf(acc[i][j][r] * sc);
;           }
.LBB0_1559:
	s_waitcnt lgkmcnt(0)
	v_mov_b32_e32 v128, v152
	s_waitcnt vmcnt(0)
	s_barrier
	v_ashrrev_i32_e32 v129, 6, v128
	v_lshrrev_b32_e32 v131, 3, v128
	v_mul_lo_u32 v130, v129, s3
	v_and_b32_e32 v131, 4, v131
	v_lshlrev_b32_e32 v132, 1, v128
	v_add_u32_e32 v130, 16, v130
	v_and_b32_e32 v132, 62, v132
	v_mul_u32_u24_e32 v131, 0x110, v131
	v_add3_u32 v131, v130, v132, v131
	v_and_b32_e32 v194, 1, v152
	v_mov_b32_e32 v193, 0x01000504
	v_mov_b32_e32 v195, 0x07060302
	v_cmp_eq_u32_e32 vcc, 1, v194
	v_mul_u32_u24_e32 v194, 0x10e, v194
	v_add_u32_e32 v192, v131, v194
	v_cndmask_b32_e32 v193, v193, v195, vcc
	v_cvt_pk_bf16_f32 v194, v112, v113
	v_cvt_pk_bf16_f32 v195, v96, v97
	v_cvt_pk_bf16_f32 v196, v80, v81
	v_cvt_pk_bf16_f32 v197, v64, v65
	v_mov_b32_dpp v198, v194 quad_perm:[1,0,3,2] row_mask:0xf bank_mask:0xf
	v_mov_b32_dpp v199, v195 quad_perm:[1,0,3,2] row_mask:0xf bank_mask:0xf
	v_mov_b32_dpp v200, v196 quad_perm:[1,0,3,2] row_mask:0xf bank_mask:0xf
	v_mov_b32_dpp v201, v197 quad_perm:[1,0,3,2] row_mask:0xf bank_mask:0xf
	v_perm_b32 v202, v194, v198, v193
	v_perm_b32 v203, v195, v199, v193
	v_perm_b32 v206, v196, v200, v193
	v_perm_b32 v207, v197, v201, v193
	ds_write_b32 v192, v202 offset:0
	ds_write_b32 v192, v203 offset:64
	ds_write_b32 v192, v206 offset:128
	ds_write_b32 v192, v207 offset:192
	v_cvt_pk_bf16_f32 v194, v114, v115
	v_cvt_pk_bf16_f32 v195, v98, v99
	v_cvt_pk_bf16_f32 v196, v82, v83
	v_cvt_pk_bf16_f32 v197, v66, v67
	v_mov_b32_dpp v198, v194 quad_perm:[1,0,3,2] row_mask:0xf bank_mask:0xf
	v_mov_b32_dpp v199, v195 quad_perm:[1,0,3,2] row_mask:0xf bank_mask:0xf
	v_mov_b32_dpp v200, v196 quad_perm:[1,0,3,2] row_mask:0xf bank_mask:0xf
	v_mov_b32_dpp v201, v197 quad_perm:[1,0,3,2] row_mask:0xf bank_mask:0xf
	v_perm_b32 v202, v194, v198, v193
	v_perm_b32 v203, v195, v199, v193
	v_perm_b32 v206, v196, v200, v193
	v_perm_b32 v207, v197, v201, v193
	ds_write_b32 v192, v202 offset:544
	ds_write_b32 v192, v203 offset:608
	ds_write_b32 v192, v206 offset:672
	ds_write_b32 v192, v207 offset:736
	v_cvt_pk_bf16_f32 v194, v116, v117
	v_cvt_pk_bf16_f32 v195, v100, v101
	v_cvt_pk_bf16_f32 v196, v84, v85
	v_cvt_pk_bf16_f32 v197, v68, v69
	v_mov_b32_dpp v198, v194 quad_perm:[1,0,3,2] row_mask:0xf bank_mask:0xf
	v_mov_b32_dpp v199, v195 quad_perm:[1,0,3,2] row_mask:0xf bank_mask:0xf
	v_mov_b32_dpp v200, v196 quad_perm:[1,0,3,2] row_mask:0xf bank_mask:0xf
	v_mov_b32_dpp v201, v197 quad_perm:[1,0,3,2] row_mask:0xf bank_mask:0xf
	v_perm_b32 v202, v194, v198, v193
	v_perm_b32 v203, v195, v199, v193
	v_perm_b32 v206, v196, v200, v193
	v_perm_b32 v207, v197, v201, v193
	ds_write_b32 v192, v202 offset:2176
	ds_write_b32 v192, v203 offset:2240
	ds_write_b32 v192, v206 offset:2304
	ds_write_b32 v192, v207 offset:2368
	v_cvt_pk_bf16_f32 v194, v118, v119
	v_cvt_pk_bf16_f32 v195, v102, v103
	v_cvt_pk_bf16_f32 v196, v86, v87
	v_cvt_pk_bf16_f32 v197, v70, v71
	v_mov_b32_dpp v198, v194 quad_perm:[1,0,3,2] row_mask:0xf bank_mask:0xf
	v_mov_b32_dpp v199, v195 quad_perm:[1,0,3,2] row_mask:0xf bank_mask:0xf
	v_mov_b32_dpp v200, v196 quad_perm:[1,0,3,2] row_mask:0xf bank_mask:0xf
	v_mov_b32_dpp v201, v197 quad_perm:[1,0,3,2] row_mask:0xf bank_mask:0xf
	v_perm_b32 v202, v194, v198, v193
	v_perm_b32 v203, v195, v199, v193
	v_perm_b32 v206, v196, v200, v193
	v_perm_b32 v207, v197, v201, v193
	ds_write_b32 v192, v202 offset:2720
	ds_write_b32 v192, v203 offset:2784
	ds_write_b32 v192, v206 offset:2848
	ds_write_b32 v192, v207 offset:2912
	v_cvt_pk_bf16_f32 v194, v120, v121
	v_cvt_pk_bf16_f32 v195, v104, v105
	v_cvt_pk_bf16_f32 v196, v88, v89
	v_cvt_pk_bf16_f32 v197, v72, v73
	v_mov_b32_dpp v198, v194 quad_perm:[1,0,3,2] row_mask:0xf bank_mask:0xf
	v_mov_b32_dpp v199, v195 quad_perm:[1,0,3,2] row_mask:0xf bank_mask:0xf
	v_mov_b32_dpp v200, v196 quad_perm:[1,0,3,2] row_mask:0xf bank_mask:0xf
	v_mov_b32_dpp v201, v197 quad_perm:[1,0,3,2] row_mask:0xf bank_mask:0xf
	v_perm_b32 v202, v194, v198, v193
	v_perm_b32 v203, v195, v199, v193
	v_perm_b32 v206, v196, v200, v193
	v_perm_b32 v207, v197, v201, v193
	ds_write_b32 v192, v202 offset:4352
	ds_write_b32 v192, v203 offset:4416
	ds_write_b32 v192, v206 offset:4480
	ds_write_b32 v192, v207 offset:4544
	v_cvt_pk_bf16_f32 v194, v122, v123
	v_cvt_pk_bf16_f32 v195, v106, v107
	v_cvt_pk_bf16_f32 v196, v90, v91
	v_cvt_pk_bf16_f32 v197, v74, v75
	v_mov_b32_dpp v198, v194 quad_perm:[1,0,3,2] row_mask:0xf bank_mask:0xf
	v_mov_b32_dpp v199, v195 quad_perm:[1,0,3,2] row_mask:0xf bank_mask:0xf
	v_mov_b32_dpp v200, v196 quad_perm:[1,0,3,2] row_mask:0xf bank_mask:0xf
	v_mov_b32_dpp v201, v197 quad_perm:[1,0,3,2] row_mask:0xf bank_mask:0xf
	v_perm_b32 v202, v194, v198, v193
	v_perm_b32 v203, v195, v199, v193
	v_perm_b32 v206, v196, v200, v193
	v_perm_b32 v207, v197, v201, v193
	ds_write_b32 v192, v202 offset:4896
	ds_write_b32 v192, v203 offset:4960
	ds_write_b32 v192, v206 offset:5024
	ds_write_b32 v192, v207 offset:5088
	v_cvt_pk_bf16_f32 v194, v124, v125
	v_cvt_pk_bf16_f32 v195, v108, v109
	v_cvt_pk_bf16_f32 v196, v92, v93
	v_cvt_pk_bf16_f32 v197, v76, v77
	v_mov_b32_dpp v198, v194 quad_perm:[1,0,3,2] row_mask:0xf bank_mask:0xf
	v_mov_b32_dpp v199, v195 quad_perm:[1,0,3,2] row_mask:0xf bank_mask:0xf
	v_mov_b32_dpp v200, v196 quad_perm:[1,0,3,2] row_mask:0xf bank_mask:0xf
	v_mov_b32_dpp v201, v197 quad_perm:[1,0,3,2] row_mask:0xf bank_mask:0xf
	v_perm_b32 v202, v194, v198, v193
	v_perm_b32 v203, v195, v199, v193
	v_perm_b32 v206, v196, v200, v193
	v_perm_b32 v207, v197, v201, v193
	ds_write_b32 v192, v202 offset:6528
	ds_write_b32 v192, v203 offset:6592
	ds_write_b32 v192, v206 offset:6656
	ds_write_b32 v192, v207 offset:6720
; __device__ __forceinline__ void gemm_nt_phase(const u16* A, int lda, const u16* Bt, int ldb, u16* C, int ldc,
;                               int Mt, int Nt, int K, int qcols, float qscale, u16* smem,
;                               u16* vtx = nullptr, u16* vtc = nullptr, u16* smv = nullptr) {
;     ...
;       char* wb = reinterpret_cast<char*>(smem) + wid * 17408;
; #pragma unroll
;       for (int i = 0; i < 2; ++i)
; #pragma unroll
;         for (int j = 0; j < 4; ++j)
; #pragma unroll
;           for (int r = 0; r < 16; ++r) {
;             const int row = i * 32 + (r & 3) + 8 * (r >> 2) + 4 * (lane >> 5);
;             const int col = j * 32 + (lane & 31);
;             *reinterpret_cast<u16*>(wb + row * 272 + col * 2) = f2bf(acc[i][j][r] * sc);
;           }
;       asm volatile("s_waitcnt lgkmcnt(0)" ::: "memory");
	v_cvt_pk_bf16_f32 v194, v126, v127
	v_cvt_pk_bf16_f32 v195, v110, v111
	v_cvt_pk_bf16_f32 v196, v94, v95
	v_cvt_pk_bf16_f32 v197, v78, v79
	v_mov_b32_dpp v198, v194 quad_perm:[1,0,3,2] row_mask:0xf bank_mask:0xf
	v_mov_b32_dpp v199, v195 quad_perm:[1,0,3,2] row_mask:0xf bank_mask:0xf
	v_mov_b32_dpp v200, v196 quad_perm:[1,0,3,2] row_mask:0xf bank_mask:0xf
	v_mov_b32_dpp v201, v197 quad_perm:[1,0,3,2] row_mask:0xf bank_mask:0xf
	v_perm_b32 v202, v194, v198, v193
	v_perm_b32 v203, v195, v199, v193
	v_perm_b32 v206, v196, v200, v193
	v_perm_b32 v207, v197, v201, v193
	ds_write_b32 v192, v202 offset:7072
	ds_write_b32 v192, v203 offset:7136
	ds_write_b32 v192, v206 offset:7200
	ds_write_b32 v192, v207 offset:7264
	v_cvt_pk_bf16_f32 v194, v48, v49
	v_cvt_pk_bf16_f32 v195, v32, v33
	v_cvt_pk_bf16_f32 v196, v16, v17
	v_cvt_pk_bf16_f32 v197, v0, v1
	v_mov_b32_dpp v198, v194 quad_perm:[1,0,3,2] row_mask:0xf bank_mask:0xf
	v_mov_b32_dpp v199, v195 quad_perm:[1,0,3,2] row_mask:0xf bank_mask:0xf
	v_mov_b32_dpp v200, v196 quad_perm:[1,0,3,2] row_mask:0xf bank_mask:0xf
	v_mov_b32_dpp v201, v197 quad_perm:[1,0,3,2] row_mask:0xf bank_mask:0xf
	v_perm_b32 v202, v194, v198, v193
	v_perm_b32 v203, v195, v199, v193
	v_perm_b32 v206, v196, v200, v193
	v_perm_b32 v207, v197, v201, v193
	ds_write_b32 v192, v202 offset:8704
	ds_write_b32 v192, v203 offset:8768
	ds_write_b32 v192, v206 offset:8832
	ds_write_b32 v192, v207 offset:8896
	v_cvt_pk_bf16_f32 v194, v50, v51
	v_cvt_pk_bf16_f32 v195, v34, v35
	v_cvt_pk_bf16_f32 v196, v18, v19
	v_cvt_pk_bf16_f32 v197, v2, v3
	v_mov_b32_dpp v198, v194 quad_perm:[1,0,3,2] row_mask:0xf bank_mask:0xf
	v_mov_b32_dpp v199, v195 quad_perm:[1,0,3,2] row_mask:0xf bank_mask:0xf
	v_mov_b32_dpp v200, v196 quad_perm:[1,0,3,2] row_mask:0xf bank_mask:0xf
	v_mov_b32_dpp v201, v197 quad_perm:[1,0,3,2] row_mask:0xf bank_mask:0xf
	v_perm_b32 v202, v194, v198, v193
	v_perm_b32 v203, v195, v199, v193
	v_perm_b32 v206, v196, v200, v193
	v_perm_b32 v207, v197, v201, v193
	ds_write_b32 v192, v202 offset:9248
	ds_write_b32 v192, v203 offset:9312
	ds_write_b32 v192, v206 offset:9376
	ds_write_b32 v192, v207 offset:9440
	v_cvt_pk_bf16_f32 v194, v52, v53
	v_cvt_pk_bf16_f32 v195, v36, v37
	v_cvt_pk_bf16_f32 v196, v20, v21
	v_cvt_pk_bf16_f32 v197, v4, v5
	v_mov_b32_dpp v198, v194 quad_perm:[1,0,3,2] row_mask:0xf bank_mask:0xf
	v_mov_b32_dpp v199, v195 quad_perm:[1,0,3,2] row_mask:0xf bank_mask:0xf
	v_mov_b32_dpp v200, v196 quad_perm:[1,0,3,2] row_mask:0xf bank_mask:0xf
	v_mov_b32_dpp v201, v197 quad_perm:[1,0,3,2] row_mask:0xf bank_mask:0xf
	v_perm_b32 v202, v194, v198, v193
	v_perm_b32 v203, v195, v199, v193
	v_perm_b32 v206, v196, v200, v193
	v_perm_b32 v207, v197, v201, v193
	ds_write_b32 v192, v202 offset:10880
	ds_write_b32 v192, v203 offset:10944
	ds_write_b32 v192, v206 offset:11008
	ds_write_b32 v192, v207 offset:11072
	v_cvt_pk_bf16_f32 v194, v54, v55
	v_cvt_pk_bf16_f32 v195, v38, v39
	v_cvt_pk_bf16_f32 v196, v22, v23
	v_cvt_pk_bf16_f32 v197, v6, v7
	v_mov_b32_dpp v198, v194 quad_perm:[1,0,3,2] row_mask:0xf bank_mask:0xf
	v_mov_b32_dpp v199, v195 quad_perm:[1,0,3,2] row_mask:0xf bank_mask:0xf
	v_mov_b32_dpp v200, v196 quad_perm:[1,0,3,2] row_mask:0xf bank_mask:0xf
	v_mov_b32_dpp v201, v197 quad_perm:[1,0,3,2] row_mask:0xf bank_mask:0xf
	v_perm_b32 v202, v194, v198, v193
	v_perm_b32 v203, v195, v199, v193
	v_perm_b32 v206, v196, v200, v193
	v_perm_b32 v207, v197, v201, v193
	ds_write_b32 v192, v202 offset:11424
	ds_write_b32 v192, v203 offset:11488
	ds_write_b32 v192, v206 offset:11552
	ds_write_b32 v192, v207 offset:11616
	v_cvt_pk_bf16_f32 v194, v56, v57
	v_cvt_pk_bf16_f32 v195, v40, v41
	v_cvt_pk_bf16_f32 v196, v24, v25
	v_cvt_pk_bf16_f32 v197, v8, v9
	v_mov_b32_dpp v198, v194 quad_perm:[1,0,3,2] row_mask:0xf bank_mask:0xf
	v_mov_b32_dpp v199, v195 quad_perm:[1,0,3,2] row_mask:0xf bank_mask:0xf
	v_mov_b32_dpp v200, v196 quad_perm:[1,0,3,2] row_mask:0xf bank_mask:0xf
	v_mov_b32_dpp v201, v197 quad_perm:[1,0,3,2] row_mask:0xf bank_mask:0xf
	v_perm_b32 v202, v194, v198, v193
	v_perm_b32 v203, v195, v199, v193
	v_perm_b32 v206, v196, v200, v193
	v_perm_b32 v207, v197, v201, v193
	ds_write_b32 v192, v202 offset:13056
	ds_write_b32 v192, v203 offset:13120
	ds_write_b32 v192, v206 offset:13184
	ds_write_b32 v192, v207 offset:13248
	v_cvt_pk_bf16_f32 v194, v58, v59
	v_cvt_pk_bf16_f32 v195, v42, v43
	v_cvt_pk_bf16_f32 v196, v26, v27
	v_cvt_pk_bf16_f32 v197, v10, v11
	v_mov_b32_dpp v198, v194 quad_perm:[1,0,3,2] row_mask:0xf bank_mask:0xf
	v_mov_b32_dpp v199, v195 quad_perm:[1,0,3,2] row_mask:0xf bank_mask:0xf
	v_mov_b32_dpp v200, v196 quad_perm:[1,0,3,2] row_mask:0xf bank_mask:0xf
	v_mov_b32_dpp v201, v197 quad_perm:[1,0,3,2] row_mask:0xf bank_mask:0xf
	v_perm_b32 v202, v194, v198, v193
	v_perm_b32 v203, v195, v199, v193
	v_perm_b32 v206, v196, v200, v193
	v_perm_b32 v207, v197, v201, v193
	ds_write_b32 v192, v202 offset:13600
	ds_write_b32 v192, v203 offset:13664
	ds_write_b32 v192, v206 offset:13728
	ds_write_b32 v192, v207 offset:13792
	v_cvt_pk_bf16_f32 v194, v60, v61
	v_cvt_pk_bf16_f32 v195, v44, v45
	v_cvt_pk_bf16_f32 v196, v28, v29
	v_cvt_pk_bf16_f32 v197, v12, v13
	v_mov_b32_dpp v198, v194 quad_perm:[1,0,3,2] row_mask:0xf bank_mask:0xf
	v_mov_b32_dpp v199, v195 quad_perm:[1,0,3,2] row_mask:0xf bank_mask:0xf
	v_mov_b32_dpp v200, v196 quad_perm:[1,0,3,2] row_mask:0xf bank_mask:0xf
	v_mov_b32_dpp v201, v197 quad_perm:[1,0,3,2] row_mask:0xf bank_mask:0xf
	v_perm_b32 v202, v194, v198, v193
	v_perm_b32 v203, v195, v199, v193
	v_perm_b32 v206, v196, v200, v193
	v_perm_b32 v207, v197, v201, v193
	ds_write_b32 v192, v202 offset:15232
	ds_write_b32 v192, v203 offset:15296
	ds_write_b32 v192, v206 offset:15360
	ds_write_b32 v192, v207 offset:15424
	v_cvt_pk_bf16_f32 v194, v62, v63
	v_cvt_pk_bf16_f32 v195, v46, v47
	v_cvt_pk_bf16_f32 v196, v30, v31
	v_cvt_pk_bf16_f32 v197, v14, v15
	v_mov_b32_dpp v198, v194 quad_perm:[1,0,3,2] row_mask:0xf bank_mask:0xf
	v_mov_b32_dpp v199, v195 quad_perm:[1,0,3,2] row_mask:0xf bank_mask:0xf
	v_mov_b32_dpp v200, v196 quad_perm:[1,0,3,2] row_mask:0xf bank_mask:0xf
	v_mov_b32_dpp v201, v197 quad_perm:[1,0,3,2] row_mask:0xf bank_mask:0xf
	v_perm_b32 v202, v194, v198, v193
	v_perm_b32 v203, v195, v199, v193
	v_perm_b32 v206, v196, v200, v193
	v_perm_b32 v207, v197, v201, v193
	ds_write_b32 v192, v202 offset:15776
	ds_write_b32 v192, v203 offset:15840
	ds_write_b32 v192, v206 offset:15904
	ds_write_b32 v192, v207 offset:15968
	v_and_b32_e32 v0, 15, v128
	v_bfe_u32 v7, v128, 4, 2
	s_lshl_b32 s6, s6, 8
	s_lshl_b64 s[8:9], s[8:9], 1
	v_lshlrev_b32_e32 v1, 4, v0
	v_lshlrev_b32_e32 v6, 3, v0
	v_mul_u32_u24_e32 v0, 0x110, v7
	s_add_u32 s8, s88, s8
	s_waitcnt lgkmcnt(0)
; __device__ __forceinline__ void gemm_nt_phase(const u16* A, int lda, const u16* Bt, int ldb, u16* C, int ldc,
;                               int Mt, int Nt, int K, int qcols, float qscale, u16* smem,
;                               u16* vtx = nullptr, u16* vtc = nullptr, u16* smv = nullptr) {
;     ...
;       asm volatile("s_waitcnt lgkmcnt(0)" ::: "memory");
; #pragma unroll
;       for (int q = 0; q < 16; ++q) {
;         const int idx = q * 64 + lane, row = idx >> 4, c16 = idx & 15;
;         const uint4 v = *reinterpret_cast<const uint4*>(wb + row * 272 + c16 * 16);
;         *reinterpret_cast<uint4*>(&Cb[(unsigned)((wm * 64 + row) * ldc + wn * 128 + c16 * 8)]) = v;
;       }
;     }
;     __syncthreads();
	v_lshrrev_b32_e32 v4, 1, v128
	v_lshlrev_b32_e32 v2, 7, v129
	v_add3_u32 v10, v130, v1, v0
	s_addc_u32 s9, s89, s9
	s_ashr_i32 s7, s6, 31
	v_and_b32_e32 v5, 0x80, v2
	ds_read_b128 v[0:3], v10
	v_and_or_b32 v4, v4, s16, v7
	s_lshl_b64 s[6:7], s[6:7], 1
	v_lshlrev_b32_e32 v4, 10, v4
	s_add_u32 s6, s8, s6
	v_or3_b32 v154, v5, v6, v4
	ds_read_b128 v[4:7], v10 offset:1088
	s_addc_u32 s7, s9, s7
	v_lshl_add_u64 v[8:9], v[154:155], 1, s[6:7]
	s_waitcnt lgkmcnt(1)
	global_store_dwordx4 v[8:9], v[0:3], off
	s_add_i32 s17, s17, s96
	s_cmpk_lt_i32 s17, 0x200
	v_or_b32_e32 v0, 0x1000, v154
	v_mov_b32_e32 v1, v155
	v_lshl_add_u64 v[0:1], v[0:1], 1, s[6:7]
	s_waitcnt lgkmcnt(0)
	global_store_dwordx4 v[0:1], v[4:7], off
	ds_read_b128 v[0:3], v10 offset:2176
	s_nop 0
	v_or_b32_e32 v4, 0x2000, v154
	v_mov_b32_e32 v5, v155
	v_lshl_add_u64 v[8:9], v[4:5], 1, s[6:7]
	ds_read_b128 v[4:7], v10 offset:3264
	s_waitcnt lgkmcnt(1)
	global_store_dwordx4 v[8:9], v[0:3], off
	s_nop 1
	v_or_b32_e32 v0, 0x3000, v154
	v_mov_b32_e32 v1, v155
	v_lshl_add_u64 v[0:1], v[0:1], 1, s[6:7]
	s_waitcnt lgkmcnt(0)
	global_store_dwordx4 v[0:1], v[4:7], off
	ds_read_b128 v[0:3], v10 offset:4352
	s_nop 0
	v_or_b32_e32 v4, 0x4000, v154
	v_mov_b32_e32 v5, v155
	v_lshl_add_u64 v[8:9], v[4:5], 1, s[6:7]
	ds_read_b128 v[4:7], v10 offset:5440
	s_waitcnt lgkmcnt(1)
	global_store_dwordx4 v[8:9], v[0:3], off
	s_nop 1
	v_or_b32_e32 v0, 0x5000, v154
	v_mov_b32_e32 v1, v155
	v_lshl_add_u64 v[0:1], v[0:1], 1, s[6:7]
	s_waitcnt lgkmcnt(0)
	global_store_dwordx4 v[0:1], v[4:7], off
	ds_read_b128 v[0:3], v10 offset:6528
	s_nop 0
	v_or_b32_e32 v4, 0x6000, v154
	v_mov_b32_e32 v5, v155
	v_lshl_add_u64 v[8:9], v[4:5], 1, s[6:7]
	ds_read_b128 v[4:7], v10 offset:7616
	s_waitcnt lgkmcnt(1)
	global_store_dwordx4 v[8:9], v[0:3], off
	s_nop 1
	v_or_b32_e32 v0, 0x7000, v154
	v_mov_b32_e32 v1, v155
	v_lshl_add_u64 v[0:1], v[0:1], 1, s[6:7]
	s_waitcnt lgkmcnt(0)
	global_store_dwordx4 v[0:1], v[4:7], off
	ds_read_b128 v[0:3], v10 offset:8704
	s_nop 0
	v_or_b32_e32 v4, 0x8000, v154
	v_mov_b32_e32 v5, v155
	v_lshl_add_u64 v[8:9], v[4:5], 1, s[6:7]
	ds_read_b128 v[4:7], v10 offset:9792
	s_waitcnt lgkmcnt(1)
	global_store_dwordx4 v[8:9], v[0:3], off
	s_nop 1
	v_or_b32_e32 v0, 0x9000, v154
	v_mov_b32_e32 v1, v155
	v_lshl_add_u64 v[0:1], v[0:1], 1, s[6:7]
	s_waitcnt lgkmcnt(0)
	global_store_dwordx4 v[0:1], v[4:7], off
	ds_read_b128 v[0:3], v10 offset:10880
	s_nop 0
	v_or_b32_e32 v4, 0xa000, v154
	v_mov_b32_e32 v5, v155
	v_lshl_add_u64 v[8:9], v[4:5], 1, s[6:7]
	ds_read_b128 v[4:7], v10 offset:11968
	s_waitcnt lgkmcnt(1)
	global_store_dwordx4 v[8:9], v[0:3], off
	s_nop 1
	v_or_b32_e32 v0, 0xb000, v154
	v_mov_b32_e32 v1, v155
	v_lshl_add_u64 v[0:1], v[0:1], 1, s[6:7]
	s_waitcnt lgkmcnt(0)
	global_store_dwordx4 v[0:1], v[4:7], off
	ds_read_b128 v[0:3], v10 offset:13056
	s_nop 0
	v_or_b32_e32 v4, 0xc000, v154
	v_mov_b32_e32 v5, v155
	v_lshl_add_u64 v[8:9], v[4:5], 1, s[6:7]
	ds_read_b128 v[4:7], v10 offset:14144
	s_waitcnt lgkmcnt(1)
	global_store_dwordx4 v[8:9], v[0:3], off
	v_or_b32_e32 v8, 0xe000, v154
	v_mov_b32_e32 v9, v155
	v_or_b32_e32 v0, 0xd000, v154
	v_mov_b32_e32 v1, v155
	v_lshl_add_u64 v[0:1], v[0:1], 1, s[6:7]
	s_waitcnt lgkmcnt(0)
	global_store_dwordx4 v[0:1], v[4:7], off
	ds_read_b128 v[0:3], v10 offset:15232
	ds_read_b128 v[4:7], v10 offset:16320
	v_lshl_add_u64 v[8:9], v[8:9], 1, s[6:7]
	v_or_b32_e32 v154, 0xf000, v154
	s_waitcnt lgkmcnt(1)
	global_store_dwordx4 v[8:9], v[0:3], off
	s_nop 1
	v_lshl_add_u64 v[0:1], v[154:155], 1, s[6:7]
	s_waitcnt lgkmcnt(0)
	global_store_dwordx4 v[0:1], v[4:7], off
	s_barrier
	s_cbranch_scc0 .LBB0_1608

; __device__ __forceinline__ void gemm_nt_phase(const u16* A, int lda, const u16* Bt, int ldb, u16* C, int ldc,
;                               int Mt, int Nt, int K, int qcols, float qscale, u16* smem,
;                               u16* vtx = nullptr, u16* vtc = nullptr, u16* smv = nullptr) {
;     ...
;     int tid_ = threadIdx.x;
;     asm volatile("" : "+v"(tid_));
;     const int lane = tid_ & 63, wid = tid_ >> 6, wm = wid >> 1, wn = wid & 1;
;     if (vtx != nullptr && nt >= 8) {
;       u16* dst; unsigned tstride;
;       if (mt < 128) { dst = vtx + (long)(mt >> 5) * 1024 * 8192 + (mt & 31) * 256; tstride = 8192; }
;       else          { dst = vtc + (long)(mt - 128) * 1024 * 256; tstride = 256; }
; #pragma unroll
;       for (int i = 0; i < 2; ++i)
; #pragma unroll
;         for (int j = 0; j < 4; ++j)
; #pragma unroll
;           for (int rq = 0; rq < 4; ++rq) {
;             const int row = wm * 64 + i * 32 + 8 * rq + 4 * (lane >> 5);
;             const int hd = (nt - 8) * 256 + wn * 128 + j * 32 + (lane & 31);
;             const unsigned v0 = f2bf(acc[i][j][4 * rq + 0]), v1 = f2bf(acc[i][j][4 * rq + 1]);
;             const unsigned v2 = f2bf(acc[i][j][4 * rq + 2]), v3 = f2bf(acc[i][j][4 * rq + 3]);
;             *reinterpret_cast<uint2*>(&dst[(unsigned)(hd * tstride + row)]) = make_uint2(v0 | (v1 << 16), v2 | (v3 << 16));
;           }
;     } else {
;       char* wb = reinterpret_cast<char*>(smem) + wid * 17408;
; #pragma unroll
;       for (int i = 0; i < 2; ++i)
; #pragma unroll
;         for (int j = 0; j < 4; ++j)
; #pragma unroll
;           for (int r = 0; r < 16; ++r) {
;             const int row = i * 32 + (r & 3) + 8 * (r >> 2) + 4 * (lane >> 5);
;             const int col = j * 32 + (lane & 31);
;             *reinterpret_cast<u16*>(wb + row * 272 + col * 2) = f2bf(acc[i][j][r] * sc);
;           }
.LBB0_1843:
	s_waitcnt lgkmcnt(0)
	v_mov_b32_e32 v128, v152
	s_waitcnt vmcnt(0)
	s_barrier
	v_ashrrev_i32_e32 v129, 6, v128
	v_lshrrev_b32_e32 v131, 3, v128
	v_mul_lo_u32 v130, v129, s15
	v_and_b32_e32 v131, 4, v131
	v_lshlrev_b32_e32 v132, 1, v128
	v_add_u32_e32 v130, 16, v130
	v_and_b32_e32 v132, 62, v132
	v_mul_u32_u24_e32 v131, 0x110, v131
	v_add3_u32 v131, v130, v132, v131
	v_and_b32_e32 v194, 1, v152
	v_mov_b32_e32 v193, 0x01000504
	v_mov_b32_e32 v195, 0x07060302
	v_cmp_eq_u32_e32 vcc, 1, v194
	v_mul_u32_u24_e32 v194, 0x10e, v194
	v_add_u32_e32 v192, v131, v194
	v_cndmask_b32_e32 v193, v193, v195, vcc
	v_cvt_pk_bf16_f32 v194, v112, v113
	v_cvt_pk_bf16_f32 v195, v96, v97
	v_cvt_pk_bf16_f32 v196, v80, v81
	v_cvt_pk_bf16_f32 v197, v64, v65
	v_mov_b32_dpp v198, v194 quad_perm:[1,0,3,2] row_mask:0xf bank_mask:0xf
	v_mov_b32_dpp v199, v195 quad_perm:[1,0,3,2] row_mask:0xf bank_mask:0xf
	v_mov_b32_dpp v200, v196 quad_perm:[1,0,3,2] row_mask:0xf bank_mask:0xf
	v_mov_b32_dpp v201, v197 quad_perm:[1,0,3,2] row_mask:0xf bank_mask:0xf
	v_perm_b32 v202, v194, v198, v193
	v_perm_b32 v203, v195, v199, v193
	v_perm_b32 v206, v196, v200, v193
	v_perm_b32 v207, v197, v201, v193
	ds_write_b32 v192, v202 offset:0
	ds_write_b32 v192, v203 offset:64
	ds_write_b32 v192, v206 offset:128
	ds_write_b32 v192, v207 offset:192
	v_cvt_pk_bf16_f32 v194, v114, v115
	v_cvt_pk_bf16_f32 v195, v98, v99
	v_cvt_pk_bf16_f32 v196, v82, v83
	v_cvt_pk_bf16_f32 v197, v66, v67
	v_mov_b32_dpp v198, v194 quad_perm:[1,0,3,2] row_mask:0xf bank_mask:0xf
	v_mov_b32_dpp v199, v195 quad_perm:[1,0,3,2] row_mask:0xf bank_mask:0xf
	v_mov_b32_dpp v200, v196 quad_perm:[1,0,3,2] row_mask:0xf bank_mask:0xf
	v_mov_b32_dpp v201, v197 quad_perm:[1,0,3,2] row_mask:0xf bank_mask:0xf
	v_perm_b32 v202, v194, v198, v193
	v_perm_b32 v203, v195, v199, v193
	v_perm_b32 v206, v196, v200, v193
	v_perm_b32 v207, v197, v201, v193
	ds_write_b32 v192, v202 offset:544
	ds_write_b32 v192, v203 offset:608
	ds_write_b32 v192, v206 offset:672
	ds_write_b32 v192, v207 offset:736
	v_cvt_pk_bf16_f32 v194, v116, v117
	v_cvt_pk_bf16_f32 v195, v100, v101
	v_cvt_pk_bf16_f32 v196, v84, v85
	v_cvt_pk_bf16_f32 v197, v68, v69
	v_mov_b32_dpp v198, v194 quad_perm:[1,0,3,2] row_mask:0xf bank_mask:0xf
	v_mov_b32_dpp v199, v195 quad_perm:[1,0,3,2] row_mask:0xf bank_mask:0xf
	v_mov_b32_dpp v200, v196 quad_perm:[1,0,3,2] row_mask:0xf bank_mask:0xf
	v_mov_b32_dpp v201, v197 quad_perm:[1,0,3,2] row_mask:0xf bank_mask:0xf
	v_perm_b32 v202, v194, v198, v193
	v_perm_b32 v203, v195, v199, v193
	v_perm_b32 v206, v196, v200, v193
	v_perm_b32 v207, v197, v201, v193
	ds_write_b32 v192, v202 offset:2176
	ds_write_b32 v192, v203 offset:2240
	ds_write_b32 v192, v206 offset:2304
	ds_write_b32 v192, v207 offset:2368
	v_cvt_pk_bf16_f32 v194, v118, v119
	v_cvt_pk_bf16_f32 v195, v102, v103
	v_cvt_pk_bf16_f32 v196, v86, v87
	v_cvt_pk_bf16_f32 v197, v70, v71
	v_mov_b32_dpp v198, v194 quad_perm:[1,0,3,2] row_mask:0xf bank_mask:0xf
	v_mov_b32_dpp v199, v195 quad_perm:[1,0,3,2] row_mask:0xf bank_mask:0xf
	v_mov_b32_dpp v200, v196 quad_perm:[1,0,3,2] row_mask:0xf bank_mask:0xf
	v_mov_b32_dpp v201, v197 quad_perm:[1,0,3,2] row_mask:0xf bank_mask:0xf
	v_perm_b32 v202, v194, v198, v193
	v_perm_b32 v203, v195, v199, v193
	v_perm_b32 v206, v196, v200, v193
	v_perm_b32 v207, v197, v201, v193
	ds_write_b32 v192, v202 offset:2720
	ds_write_b32 v192, v203 offset:2784
	ds_write_b32 v192, v206 offset:2848
	ds_write_b32 v192, v207 offset:2912
	v_cvt_pk_bf16_f32 v194, v120, v121
	v_cvt_pk_bf16_f32 v195, v104, v105
	v_cvt_pk_bf16_f32 v196, v88, v89
	v_cvt_pk_bf16_f32 v197, v72, v73
	v_mov_b32_dpp v198, v194 quad_perm:[1,0,3,2] row_mask:0xf bank_mask:0xf
	v_mov_b32_dpp v199, v195 quad_perm:[1,0,3,2] row_mask:0xf bank_mask:0xf
	v_mov_b32_dpp v200, v196 quad_perm:[1,0,3,2] row_mask:0xf bank_mask:0xf
	v_mov_b32_dpp v201, v197 quad_perm:[1,0,3,2] row_mask:0xf bank_mask:0xf
	v_perm_b32 v202, v194, v198, v193
	v_perm_b32 v203, v195, v199, v193
	v_perm_b32 v206, v196, v200, v193
	v_perm_b32 v207, v197, v201, v193
	ds_write_b32 v192, v202 offset:4352
	ds_write_b32 v192, v203 offset:4416
	ds_write_b32 v192, v206 offset:4480
	ds_write_b32 v192, v207 offset:4544
	v_cvt_pk_bf16_f32 v194, v122, v123
	v_cvt_pk_bf16_f32 v195, v106, v107
	v_cvt_pk_bf16_f32 v196, v90, v91
	v_cvt_pk_bf16_f32 v197, v74, v75
	v_mov_b32_dpp v198, v194 quad_perm:[1,0,3,2] row_mask:0xf bank_mask:0xf
	v_mov_b32_dpp v199, v195 quad_perm:[1,0,3,2] row_mask:0xf bank_mask:0xf
	v_mov_b32_dpp v200, v196 quad_perm:[1,0,3,2] row_mask:0xf bank_mask:0xf
	v_mov_b32_dpp v201, v197 quad_perm:[1,0,3,2] row_mask:0xf bank_mask:0xf
	v_perm_b32 v202, v194, v198, v193
	v_perm_b32 v203, v195, v199, v193
	v_perm_b32 v206, v196, v200, v193
	v_perm_b32 v207, v197, v201, v193
	ds_write_b32 v192, v202 offset:4896
	ds_write_b32 v192, v203 offset:4960
	ds_write_b32 v192, v206 offset:5024
	ds_write_b32 v192, v207 offset:5088
	v_cvt_pk_bf16_f32 v194, v124, v125
	v_cvt_pk_bf16_f32 v195, v108, v109
	v_cvt_pk_bf16_f32 v196, v92, v93
	v_cvt_pk_bf16_f32 v197, v76, v77
	v_mov_b32_dpp v198, v194 quad_perm:[1,0,3,2] row_mask:0xf bank_mask:0xf
	v_mov_b32_dpp v199, v195 quad_perm:[1,0,3,2] row_mask:0xf bank_mask:0xf
	v_mov_b32_dpp v200, v196 quad_perm:[1,0,3,2] row_mask:0xf bank_mask:0xf
	v_mov_b32_dpp v201, v197 quad_perm:[1,0,3,2] row_mask:0xf bank_mask:0xf
	v_perm_b32 v202, v194, v198, v193
	v_perm_b32 v203, v195, v199, v193
	v_perm_b32 v206, v196, v200, v193
	v_perm_b32 v207, v197, v201, v193
	ds_write_b32 v192, v202 offset:6528
	ds_write_b32 v192, v203 offset:6592
	ds_write_b32 v192, v206 offset:6656
	ds_write_b32 v192, v207 offset:6720
; __device__ __forceinline__ void gemm_nt_phase(const u16* A, int lda, const u16* Bt, int ldb, u16* C, int ldc,
;                               int Mt, int Nt, int K, int qcols, float qscale, u16* smem,
;                               u16* vtx = nullptr, u16* vtc = nullptr, u16* smv = nullptr) {
;     ...
;       char* wb = reinterpret_cast<char*>(smem) + wid * 17408;
; #pragma unroll
;       for (int i = 0; i < 2; ++i)
; #pragma unroll
;         for (int j = 0; j < 4; ++j)
; #pragma unroll
;           for (int r = 0; r < 16; ++r) {
;             const int row = i * 32 + (r & 3) + 8 * (r >> 2) + 4 * (lane >> 5);
;             const int col = j * 32 + (lane & 31);
;             *reinterpret_cast<u16*>(wb + row * 272 + col * 2) = f2bf(acc[i][j][r] * sc);
;           }
;       asm volatile("s_waitcnt lgkmcnt(0)" ::: "memory");
	v_cvt_pk_bf16_f32 v194, v126, v127
	v_cvt_pk_bf16_f32 v195, v110, v111
	v_cvt_pk_bf16_f32 v196, v94, v95
	v_cvt_pk_bf16_f32 v197, v78, v79
	v_mov_b32_dpp v198, v194 quad_perm:[1,0,3,2] row_mask:0xf bank_mask:0xf
	v_mov_b32_dpp v199, v195 quad_perm:[1,0,3,2] row_mask:0xf bank_mask:0xf
	v_mov_b32_dpp v200, v196 quad_perm:[1,0,3,2] row_mask:0xf bank_mask:0xf
	v_mov_b32_dpp v201, v197 quad_perm:[1,0,3,2] row_mask:0xf bank_mask:0xf
	v_perm_b32 v202, v194, v198, v193
	v_perm_b32 v203, v195, v199, v193
	v_perm_b32 v206, v196, v200, v193
	v_perm_b32 v207, v197, v201, v193
	ds_write_b32 v192, v202 offset:7072
	ds_write_b32 v192, v203 offset:7136
	ds_write_b32 v192, v206 offset:7200
	ds_write_b32 v192, v207 offset:7264
	v_cvt_pk_bf16_f32 v194, v48, v49
	v_cvt_pk_bf16_f32 v195, v32, v33
	v_cvt_pk_bf16_f32 v196, v16, v17
	v_cvt_pk_bf16_f32 v197, v0, v1
	v_mov_b32_dpp v198, v194 quad_perm:[1,0,3,2] row_mask:0xf bank_mask:0xf
	v_mov_b32_dpp v199, v195 quad_perm:[1,0,3,2] row_mask:0xf bank_mask:0xf
	v_mov_b32_dpp v200, v196 quad_perm:[1,0,3,2] row_mask:0xf bank_mask:0xf
	v_mov_b32_dpp v201, v197 quad_perm:[1,0,3,2] row_mask:0xf bank_mask:0xf
	v_perm_b32 v202, v194, v198, v193
	v_perm_b32 v203, v195, v199, v193
	v_perm_b32 v206, v196, v200, v193
	v_perm_b32 v207, v197, v201, v193
	ds_write_b32 v192, v202 offset:8704
	ds_write_b32 v192, v203 offset:8768
	ds_write_b32 v192, v206 offset:8832
	ds_write_b32 v192, v207 offset:8896
	v_cvt_pk_bf16_f32 v194, v50, v51
	v_cvt_pk_bf16_f32 v195, v34, v35
	v_cvt_pk_bf16_f32 v196, v18, v19
	v_cvt_pk_bf16_f32 v197, v2, v3
	v_mov_b32_dpp v198, v194 quad_perm:[1,0,3,2] row_mask:0xf bank_mask:0xf
	v_mov_b32_dpp v199, v195 quad_perm:[1,0,3,2] row_mask:0xf bank_mask:0xf
	v_mov_b32_dpp v200, v196 quad_perm:[1,0,3,2] row_mask:0xf bank_mask:0xf
	v_mov_b32_dpp v201, v197 quad_perm:[1,0,3,2] row_mask:0xf bank_mask:0xf
	v_perm_b32 v202, v194, v198, v193
	v_perm_b32 v203, v195, v199, v193
	v_perm_b32 v206, v196, v200, v193
	v_perm_b32 v207, v197, v201, v193
	ds_write_b32 v192, v202 offset:9248
	ds_write_b32 v192, v203 offset:9312
	ds_write_b32 v192, v206 offset:9376
	ds_write_b32 v192, v207 offset:9440
	v_cvt_pk_bf16_f32 v194, v52, v53
	v_cvt_pk_bf16_f32 v195, v36, v37
	v_cvt_pk_bf16_f32 v196, v20, v21
	v_cvt_pk_bf16_f32 v197, v4, v5
	v_mov_b32_dpp v198, v194 quad_perm:[1,0,3,2] row_mask:0xf bank_mask:0xf
	v_mov_b32_dpp v199, v195 quad_perm:[1,0,3,2] row_mask:0xf bank_mask:0xf
	v_mov_b32_dpp v200, v196 quad_perm:[1,0,3,2] row_mask:0xf bank_mask:0xf
	v_mov_b32_dpp v201, v197 quad_perm:[1,0,3,2] row_mask:0xf bank_mask:0xf
	v_perm_b32 v202, v194, v198, v193
	v_perm_b32 v203, v195, v199, v193
	v_perm_b32 v206, v196, v200, v193
	v_perm_b32 v207, v197, v201, v193
	ds_write_b32 v192, v202 offset:10880
	ds_write_b32 v192, v203 offset:10944
	ds_write_b32 v192, v206 offset:11008
	ds_write_b32 v192, v207 offset:11072
	v_cvt_pk_bf16_f32 v194, v54, v55
	v_cvt_pk_bf16_f32 v195, v38, v39
	v_cvt_pk_bf16_f32 v196, v22, v23
	v_cvt_pk_bf16_f32 v197, v6, v7
	v_mov_b32_dpp v198, v194 quad_perm:[1,0,3,2] row_mask:0xf bank_mask:0xf
	v_mov_b32_dpp v199, v195 quad_perm:[1,0,3,2] row_mask:0xf bank_mask:0xf
	v_mov_b32_dpp v200, v196 quad_perm:[1,0,3,2] row_mask:0xf bank_mask:0xf
	v_mov_b32_dpp v201, v197 quad_perm:[1,0,3,2] row_mask:0xf bank_mask:0xf
	v_perm_b32 v202, v194, v198, v193
	v_perm_b32 v203, v195, v199, v193
	v_perm_b32 v206, v196, v200, v193
	v_perm_b32 v207, v197, v201, v193
	ds_write_b32 v192, v202 offset:11424
	ds_write_b32 v192, v203 offset:11488
	ds_write_b32 v192, v206 offset:11552
	ds_write_b32 v192, v207 offset:11616
	v_cvt_pk_bf16_f32 v194, v56, v57
	v_cvt_pk_bf16_f32 v195, v40, v41
	v_cvt_pk_bf16_f32 v196, v24, v25
	v_cvt_pk_bf16_f32 v197, v8, v9
	v_mov_b32_dpp v198, v194 quad_perm:[1,0,3,2] row_mask:0xf bank_mask:0xf
	v_mov_b32_dpp v199, v195 quad_perm:[1,0,3,2] row_mask:0xf bank_mask:0xf
	v_mov_b32_dpp v200, v196 quad_perm:[1,0,3,2] row_mask:0xf bank_mask:0xf
	v_mov_b32_dpp v201, v197 quad_perm:[1,0,3,2] row_mask:0xf bank_mask:0xf
	v_perm_b32 v202, v194, v198, v193
	v_perm_b32 v203, v195, v199, v193
	v_perm_b32 v206, v196, v200, v193
	v_perm_b32 v207, v197, v201, v193
	ds_write_b32 v192, v202 offset:13056
	ds_write_b32 v192, v203 offset:13120
	ds_write_b32 v192, v206 offset:13184
	ds_write_b32 v192, v207 offset:13248
	v_cvt_pk_bf16_f32 v194, v58, v59
	v_cvt_pk_bf16_f32 v195, v42, v43
	v_cvt_pk_bf16_f32 v196, v26, v27
	v_cvt_pk_bf16_f32 v197, v10, v11
	v_mov_b32_dpp v198, v194 quad_perm:[1,0,3,2] row_mask:0xf bank_mask:0xf
	v_mov_b32_dpp v199, v195 quad_perm:[1,0,3,2] row_mask:0xf bank_mask:0xf
	v_mov_b32_dpp v200, v196 quad_perm:[1,0,3,2] row_mask:0xf bank_mask:0xf
	v_mov_b32_dpp v201, v197 quad_perm:[1,0,3,2] row_mask:0xf bank_mask:0xf
	v_perm_b32 v202, v194, v198, v193
	v_perm_b32 v203, v195, v199, v193
	v_perm_b32 v206, v196, v200, v193
	v_perm_b32 v207, v197, v201, v193
	ds_write_b32 v192, v202 offset:13600
	ds_write_b32 v192, v203 offset:13664
	ds_write_b32 v192, v206 offset:13728
	ds_write_b32 v192, v207 offset:13792
	v_cvt_pk_bf16_f32 v194, v60, v61
	v_cvt_pk_bf16_f32 v195, v44, v45
	v_cvt_pk_bf16_f32 v196, v28, v29
	v_cvt_pk_bf16_f32 v197, v12, v13
	v_mov_b32_dpp v198, v194 quad_perm:[1,0,3,2] row_mask:0xf bank_mask:0xf
	v_mov_b32_dpp v199, v195 quad_perm:[1,0,3,2] row_mask:0xf bank_mask:0xf
	v_mov_b32_dpp v200, v196 quad_perm:[1,0,3,2] row_mask:0xf bank_mask:0xf
	v_mov_b32_dpp v201, v197 quad_perm:[1,0,3,2] row_mask:0xf bank_mask:0xf
	v_perm_b32 v202, v194, v198, v193
	v_perm_b32 v203, v195, v199, v193
	v_perm_b32 v206, v196, v200, v193
	v_perm_b32 v207, v197, v201, v193
	ds_write_b32 v192, v202 offset:15232
	ds_write_b32 v192, v203 offset:15296
	ds_write_b32 v192, v206 offset:15360
	ds_write_b32 v192, v207 offset:15424
	v_cvt_pk_bf16_f32 v194, v62, v63
	v_cvt_pk_bf16_f32 v195, v46, v47
	v_cvt_pk_bf16_f32 v196, v30, v31
	v_cvt_pk_bf16_f32 v197, v14, v15
	v_mov_b32_dpp v198, v194 quad_perm:[1,0,3,2] row_mask:0xf bank_mask:0xf
	v_mov_b32_dpp v199, v195 quad_perm:[1,0,3,2] row_mask:0xf bank_mask:0xf
	v_mov_b32_dpp v200, v196 quad_perm:[1,0,3,2] row_mask:0xf bank_mask:0xf
	v_mov_b32_dpp v201, v197 quad_perm:[1,0,3,2] row_mask:0xf bank_mask:0xf
	v_perm_b32 v202, v194, v198, v193
	v_perm_b32 v203, v195, v199, v193
	v_perm_b32 v206, v196, v200, v193
	v_perm_b32 v207, v197, v201, v193
	ds_write_b32 v192, v202 offset:15776
	ds_write_b32 v192, v203 offset:15840
	ds_write_b32 v192, v206 offset:15904
	ds_write_b32 v192, v207 offset:15968
	v_and_b32_e32 v0, 15, v128
	v_bfe_u32 v7, v128, 4, 2
	s_lshl_b32 s8, s18, 8
	s_lshl_b64 s[6:7], s[6:7], 19
	v_lshlrev_b32_e32 v1, 4, v0
	v_lshlrev_b32_e32 v6, 3, v0
	v_mul_u32_u24_e32 v0, 0x110, v7
	s_add_u32 s10, s88, s6
	s_waitcnt lgkmcnt(0)
; __device__ __forceinline__ void gemm_nt_phase(const u16* A, int lda, const u16* Bt, int ldb, u16* C, int ldc,
;                               int Mt, int Nt, int K, int qcols, float qscale, u16* smem,
;                               u16* vtx = nullptr, u16* vtc = nullptr, u16* smv = nullptr) {
;     ...
;       asm volatile("s_waitcnt lgkmcnt(0)" ::: "memory");
; #pragma unroll
;       for (int q = 0; q < 16; ++q) {
;         const int idx = q * 64 + lane, row = idx >> 4, c16 = idx & 15;
;         const uint4 v = *reinterpret_cast<const uint4*>(wb + row * 272 + c16 * 16);
;         *reinterpret_cast<uint4*>(&Cb[(unsigned)((wm * 64 + row) * ldc + wn * 128 + c16 * 8)]) = v;
;       }
;     }
;     __syncthreads();
	v_lshrrev_b32_e32 v4, 1, v128
	v_lshlrev_b32_e32 v2, 7, v129
	v_add3_u32 v10, v130, v1, v0
	s_addc_u32 s11, s89, s7
	s_ashr_i32 s9, s8, 31
	v_and_b32_e32 v5, 0x80, v2
	ds_read_b128 v[0:3], v10
	v_and_or_b32 v4, v4, s16, v7
	s_lshl_b64 s[6:7], s[8:9], 1
	v_lshlrev_b32_e32 v4, 10, v4
	s_add_u32 s6, s10, s6
	v_or3_b32 v154, v5, v6, v4
	ds_read_b128 v[4:7], v10 offset:1088
	s_addc_u32 s7, s11, s7
	v_lshl_add_u64 v[8:9], v[154:155], 1, s[6:7]
	s_waitcnt lgkmcnt(1)
	global_store_dwordx4 v[8:9], v[0:3], off
	s_add_i32 s17, s17, s96
	s_cmpk_lt_i32 s17, 0x200
	v_or_b32_e32 v0, 0x1000, v154
	v_mov_b32_e32 v1, v155
	v_lshl_add_u64 v[0:1], v[0:1], 1, s[6:7]
	s_waitcnt lgkmcnt(0)
	global_store_dwordx4 v[0:1], v[4:7], off
	ds_read_b128 v[0:3], v10 offset:2176
	s_nop 0
	v_or_b32_e32 v4, 0x2000, v154
	v_mov_b32_e32 v5, v155
	v_lshl_add_u64 v[8:9], v[4:5], 1, s[6:7]
	ds_read_b128 v[4:7], v10 offset:3264
	s_waitcnt lgkmcnt(1)
	global_store_dwordx4 v[8:9], v[0:3], off
	s_nop 1
	v_or_b32_e32 v0, 0x3000, v154
	v_mov_b32_e32 v1, v155
	v_lshl_add_u64 v[0:1], v[0:1], 1, s[6:7]
	s_waitcnt lgkmcnt(0)
	global_store_dwordx4 v[0:1], v[4:7], off
	ds_read_b128 v[0:3], v10 offset:4352
	s_nop 0
	v_or_b32_e32 v4, 0x4000, v154
	v_mov_b32_e32 v5, v155
	v_lshl_add_u64 v[8:9], v[4:5], 1, s[6:7]
	ds_read_b128 v[4:7], v10 offset:5440
	s_waitcnt lgkmcnt(1)
	global_store_dwordx4 v[8:9], v[0:3], off
	s_nop 1
	v_or_b32_e32 v0, 0x5000, v154
	v_mov_b32_e32 v1, v155
	v_lshl_add_u64 v[0:1], v[0:1], 1, s[6:7]
	s_waitcnt lgkmcnt(0)
	global_store_dwordx4 v[0:1], v[4:7], off
	ds_read_b128 v[0:3], v10 offset:6528
	s_nop 0
	v_or_b32_e32 v4, 0x6000, v154
	v_mov_b32_e32 v5, v155
	v_lshl_add_u64 v[8:9], v[4:5], 1, s[6:7]
	ds_read_b128 v[4:7], v10 offset:7616
	s_waitcnt lgkmcnt(1)
	global_store_dwordx4 v[8:9], v[0:3], off
	s_nop 1
	v_or_b32_e32 v0, 0x7000, v154
	v_mov_b32_e32 v1, v155
	v_lshl_add_u64 v[0:1], v[0:1], 1, s[6:7]
	s_waitcnt lgkmcnt(0)
	global_store_dwordx4 v[0:1], v[4:7], off
	ds_read_b128 v[0:3], v10 offset:8704
	s_nop 0
	v_or_b32_e32 v4, 0x8000, v154
	v_mov_b32_e32 v5, v155
	v_lshl_add_u64 v[8:9], v[4:5], 1, s[6:7]
	ds_read_b128 v[4:7], v10 offset:9792
	s_waitcnt lgkmcnt(1)
	global_store_dwordx4 v[8:9], v[0:3], off
	s_nop 1
	v_or_b32_e32 v0, 0x9000, v154
	v_mov_b32_e32 v1, v155
	v_lshl_add_u64 v[0:1], v[0:1], 1, s[6:7]
	s_waitcnt lgkmcnt(0)
	global_store_dwordx4 v[0:1], v[4:7], off
	ds_read_b128 v[0:3], v10 offset:10880
	s_nop 0
	v_or_b32_e32 v4, 0xa000, v154
	v_mov_b32_e32 v5, v155
	v_lshl_add_u64 v[8:9], v[4:5], 1, s[6:7]
	ds_read_b128 v[4:7], v10 offset:11968
	s_waitcnt lgkmcnt(1)
	global_store_dwordx4 v[8:9], v[0:3], off
	s_nop 1
	v_or_b32_e32 v0, 0xb000, v154
	v_mov_b32_e32 v1, v155
	v_lshl_add_u64 v[0:1], v[0:1], 1, s[6:7]
	s_waitcnt lgkmcnt(0)
	global_store_dwordx4 v[0:1], v[4:7], off
	ds_read_b128 v[0:3], v10 offset:13056
	s_nop 0
	v_or_b32_e32 v4, 0xc000, v154
	v_mov_b32_e32 v5, v155
	v_lshl_add_u64 v[8:9], v[4:5], 1, s[6:7]
	ds_read_b128 v[4:7], v10 offset:14144
	s_waitcnt lgkmcnt(1)
	global_store_dwordx4 v[8:9], v[0:3], off
	v_or_b32_e32 v8, 0xe000, v154
	v_mov_b32_e32 v9, v155
	v_or_b32_e32 v0, 0xd000, v154
	v_mov_b32_e32 v1, v155
	v_lshl_add_u64 v[0:1], v[0:1], 1, s[6:7]
	s_waitcnt lgkmcnt(0)
	global_store_dwordx4 v[0:1], v[4:7], off
	ds_read_b128 v[0:3], v10 offset:15232
	ds_read_b128 v[4:7], v10 offset:16320
	v_lshl_add_u64 v[8:9], v[8:9], 1, s[6:7]
	v_or_b32_e32 v154, 0xf000, v154
	s_waitcnt lgkmcnt(1)
	global_store_dwordx4 v[8:9], v[0:3], off
	s_nop 1
	v_lshl_add_u64 v[0:1], v[154:155], 1, s[6:7]
	s_waitcnt lgkmcnt(0)
	global_store_dwordx4 v[0:1], v[4:7], off
	s_barrier
	s_cbranch_scc0 .LBB0_1892
